# v13 + head-major dilation-folded q/k/v layout (QKV epilogue + attention loads) + Q prefetched one unit ahead + no store wait at attention loop top
# speedup vs baseline: 1.0043x; 1.0043x over previous
; __device__ __forceinline__ void attn_phase(LAS unsigned char* lds, const bf16* Qg, const bf16* Kg, const bf16* Vg  , bf16* OB, float* LSE, int g, int dsh, int u_lo, int u_hi) {
;     ...
;     if (u_lo + (int)blockIdx.x < u_hi) { ATTN_DECODE(u_lo + (int)blockIdx.x, h0, Q00, tb0) ATTN_FETCH(h0, Q00, tb0); }
.LBB0_135:
	v_readlane_b32 s4, v250, 48
	v_readlane_b32 s5, v250, 49
	s_and_b64 vcc, exec, s[4:5]
	s_cbranch_vccz .LBB0_188
	s_add_u32 s2, s34, 0x14000000
	v_readlane_b32 s4, v250, 56
	s_addc_u32 s6, s35, 0
	v_readlane_b32 s5, v250, 57
	s_and_b64 s[4:5], s[4:5], exec
	v_readlane_b32 s4, v251, 29
	s_cselect_b32 s8, s4, s6
	v_readlane_b32 s4, v251, 28
	s_cselect_b32 s9, s4, s2
	v_readlane_b32 s4, v251, 35
	v_readlane_b32 s2, v250, 58
	v_readlane_b32 s5, v251, 36
	s_add_u32 s10, s34, s2
	v_mov_b32_e32 v166, v163
	v_cndmask_b32_e64 v0, 0, 1, s[4:5]
	v_writelane_b32 v249, s62, 2
	s_addc_u32 s11, s35, 0
	v_cmp_ne_u32_e64 s[38:39], 1, v0
	s_andn2_b64 vcc, exec, s[4:5]
	v_readfirstlane_b32 s2, v166
	v_writelane_b32 v249, s63, 3
	s_cbranch_vccnz .LBB0_138
	v_readlane_b32 s100, v250, 60
	s_and_b32 s101, s100, 0xfff
	s_lshl_b32 s101, s101, 12
	s_lshr_b32 s101, s101, s30
	s_andn2_b32 s100, s100, 0xfff
	s_lshl_b32 s100, s100, 4
	s_add_i32 s100, s100, s101
	s_and_b32 s101, s78, 15
	s_lshl_b32 s101, s101, 12
	s_add_i32 s100, s100, s101
	s_mov_b32 s101, 0
	s_movk_i32 s4, 0xbff
	v_cmp_lt_i32_e32 vcc, s4, v166
	v_readlane_b32 s5, v250, 62
	v_readlane_b32 s12, v250, 60
	v_cndmask_b32_e32 v0, 0, v196, vcc
	v_add_u32_e32 v0, v0, v166
	v_ashrrev_i32_e32 v0, 3, v0
	v_add_u32_e32 v0, s5, v0
	v_max_i32_e32 v0, 0, v0
	v_lshlrev_b64 v[4:5], 0, v[0:1]
	v_readlane_b32 s13, v250, 61
	v_mov_b32_e32 v6, s8
	v_mov_b32_e32 v7, s11
	v_mov_b32_e32 v8, s9
	v_mov_b32_e32 v9, s10
	v_lshl_add_u64 v[4:5], v[4:5], 0, s[100:101]
	v_readlane_b32 s6, v250, 13
	v_cndmask_b32_e32 v3, v6, v7, vcc
	v_cndmask_b32_e32 v2, v8, v9, vcc
	v_lshlrev_b64 v[4:5], 7, v[4:5]
	v_readlane_b32 s7, v250, 14
	v_lshl_add_u64 v[2:3], v[2:3], 0, v[4:5]
	s_mov_b32 s7, s95
	v_lshlrev_b32_e32 v0, 4, v166
	v_lshl_add_u64 v[2:3], v[2:3], 0, 0
	v_and_b32_e32 v0, 0x70, v0
	s_movk_i32 s4, 0x9ff
	v_lshl_add_u64 v[2:3], v[2:3], 0, v[0:1]
	v_cmp_lt_i32_e32 vcc, s4, v166
	global_load_dwordx4 v[82:85], v[2:3], off
	v_mov_b32_e32 v3, v1
	v_cndmask_b32_e32 v2, 0, v196, vcc
	v_add3_u32 v2, v166, v2, s64
	v_ashrrev_i32_e32 v2, 3, v2
	v_add_u32_e32 v2, s5, v2
	v_max_i32_e32 v2, 0, v2
	v_lshlrev_b64 v[2:3], 0, v[2:3]
	v_lshl_add_u64 v[2:3], v[2:3], 0, s[100:101]
	v_cndmask_b32_e32 v5, v6, v7, vcc
	v_cndmask_b32_e32 v4, v8, v9, vcc
	v_lshlrev_b64 v[2:3], 7, v[2:3]
	v_lshl_add_u64 v[2:3], v[4:5], 0, v[2:3]
	v_lshl_add_u64 v[2:3], v[2:3], 0, 0
	s_movk_i32 s4, 0x7ff
	v_lshl_add_u64 v[2:3], v[2:3], 0, v[0:1]
	v_cmp_lt_i32_e32 vcc, s4, v166
	global_load_dwordx4 v[86:89], v[2:3], off
	s_movk_i32 s4, 0x400
	v_cndmask_b32_e32 v2, 0, v196, vcc
	v_add3_u32 v2, v166, v2, s4
	v_ashrrev_i32_e32 v2, 3, v2
	v_add_u32_e32 v2, s5, v2
	v_max_i32_e32 v2, 0, v2
	v_mov_b32_e32 v3, v1
	v_lshlrev_b64 v[2:3], 0, v[2:3]
	v_lshl_add_u64 v[2:3], v[2:3], 0, s[100:101]
	v_cndmask_b32_e32 v5, v6, v7, vcc
	v_cndmask_b32_e32 v4, v8, v9, vcc
	v_lshlrev_b64 v[2:3], 7, v[2:3]
	v_lshl_add_u64 v[2:3], v[4:5], 0, v[2:3]
	v_lshl_add_u64 v[2:3], v[2:3], 0, 0
	s_movk_i32 s4, 0x5ff
	v_lshl_add_u64 v[2:3], v[2:3], 0, v[0:1]
	v_cmp_lt_i32_e32 vcc, s4, v166
	global_load_dwordx4 v[90:93], v[2:3], off
	s_movk_i32 s4, 0x600
	v_cndmask_b32_e32 v2, 0, v196, vcc
	v_add3_u32 v2, v166, v2, s4
	v_ashrrev_i32_e32 v2, 3, v2
	v_add_u32_e32 v2, s5, v2
	v_max_i32_e32 v2, 0, v2
	v_mov_b32_e32 v3, v1
	v_lshlrev_b64 v[2:3], 0, v[2:3]
	v_lshl_add_u64 v[2:3], v[2:3], 0, s[100:101]
	v_cndmask_b32_e32 v5, v6, v7, vcc
	v_cndmask_b32_e32 v4, v8, v9, vcc
	v_lshlrev_b64 v[2:3], 7, v[2:3]
	v_lshl_add_u64 v[2:3], v[4:5], 0, v[2:3]
	v_lshl_add_u64 v[2:3], v[2:3], 0, 0
	s_movk_i32 s4, 0x3ff
	v_lshl_add_u64 v[2:3], v[2:3], 0, v[0:1]
	v_cmp_lt_i32_e32 vcc, s4, v166
	global_load_dwordx4 v[94:97], v[2:3], off
	s_movk_i32 s4, 0x800
	v_cndmask_b32_e32 v2, 0, v196, vcc
	v_add3_u32 v2, v166, v2, s4
	v_ashrrev_i32_e32 v2, 3, v2
	v_add_u32_e32 v2, s5, v2
	v_max_i32_e32 v2, 0, v2
	v_mov_b32_e32 v3, v1
	v_lshlrev_b64 v[2:3], 0, v[2:3]
	v_lshl_add_u64 v[2:3], v[2:3], 0, s[100:101]
	v_cndmask_b32_e32 v5, v6, v7, vcc
	v_cndmask_b32_e32 v4, v8, v9, vcc
	v_lshlrev_b64 v[2:3], 7, v[2:3]
	v_lshl_add_u64 v[2:3], v[4:5], 0, v[2:3]
	v_lshl_add_u64 v[2:3], v[2:3], 0, 0
	s_movk_i32 s4, 0x1ff
	v_lshl_add_u64 v[2:3], v[2:3], 0, v[0:1]
	v_cmp_lt_i32_e32 vcc, s4, v166
	global_load_dwordx4 v[98:101], v[2:3], off
	s_movk_i32 s4, 0xa00
	v_cndmask_b32_e32 v2, 0, v196, vcc
	v_add3_u32 v2, v166, v2, s4
	v_ashrrev_i32_e32 v2, 3, v2
	v_add_u32_e32 v2, s5, v2
	v_max_i32_e32 v2, 0, v2
	v_mov_b32_e32 v3, v1
	v_lshlrev_b64 v[2:3], 0, v[2:3]
	v_lshl_add_u64 v[2:3], v[2:3], 0, s[100:101]
	v_cndmask_b32_e32 v5, v6, v7, vcc
	v_cndmask_b32_e32 v4, v8, v9, vcc
	v_lshlrev_b64 v[2:3], 7, v[2:3]
	v_lshl_add_u64 v[2:3], v[4:5], 0, v[2:3]
	v_lshl_add_u64 v[2:3], v[2:3], 0, 0
	v_lshl_add_u64 v[2:3], v[2:3], 0, v[0:1]
	global_load_dwordx4 v[102:105], v[2:3], off
	v_add_u32_e32 v2, 0xc00, v166
	v_cmp_lt_i32_e32 vcc, -1, v166
	v_mov_b32_e32 v3, v1
	s_movk_i32 s4, 0xfdff
	v_cndmask_b32_e32 v2, v2, v166, vcc
	v_ashrrev_i32_e32 v2, 3, v2
	v_add_u32_e32 v2, s5, v2
	v_max_i32_e32 v2, 0, v2
	v_lshlrev_b64 v[2:3], 0, v[2:3]
	v_lshl_add_u64 v[2:3], v[2:3], 0, s[100:101]
	v_cndmask_b32_e32 v5, v6, v7, vcc
	v_cndmask_b32_e32 v4, v8, v9, vcc
	v_lshlrev_b64 v[2:3], 7, v[2:3]
	v_lshl_add_u64 v[2:3], v[4:5], 0, v[2:3]
; #define GAS __attribute__((address_space(1)))
; #define LAS __attribute__((address_space(3)))
; #define LDS_BAR() do { asm volatile("s_waitcnt lgkmcnt(0)" ::: "memory"); __builtin_amdgcn_s_barrier(); asm volatile("" ::: "memory"); } while (0)
; __device__ __forceinline__ void attn_phase(LAS unsigned char* lds, const bf16* Qg, const bf16* Kg, const bf16* Vg  , bf16* OB, float* LSE, int g, int dsh, int u_lo, int u_hi) {
;     ...
;     if (u_lo + (int)blockIdx.x < u_hi) { ATTN_DECODE(u_lo + (int)blockIdx.x, h0, Q00, tb0) ATTN_FETCH(h0, Q00, tb0); }
;     for (int u = u_lo + blockIdx.x; u < u_hi; u += gridDim.x) {
;         int tq_ = tid; asm volatile("" : "+v"(tq_));
;         { const int tid = tq_, lane = tid & 63, r = lane & 31, hh = lane >> 5;
;         ATTN_DECODE(u, h, Q0, tokbase)
; #pragma unroll
;         for (int it = 0; it < 12; ++it) { const int piece = tid + 512 * it; const int kv = piece >= 3072 ? 1 : 0; const int pr = piece - 3072 * kv; const int row = pr >> 3, ch = pr & 7;
;             const bool live = (Q0 - 128 + row) >= 0; v4u val = kvr[it]; if (!live) val = (v4u){0u, 0u, 0u, 0u};
;             *(LAS v4u*)((kv ? Vl : Kl) + row * AT_PITCH + ch * 16) = val; }
;         const int qpos = Q0 + 32 * wave + r; const size_t qtok = tokbase + (size_t)qpos * dil;
;         bf16x8 qf[4];
; #pragma unroll
;         for (int ks = 0; ks < 4; ++ks) qf[ks] = *(const GAS bf16x8*)(Qg + qtok * 1024 + h * 64 + 16 * ks + 8 * hh);
;         LDS_BAR();
;         { const int un0 = u + (int)gridDim.x; const int un = un0 < u_hi ? un0 : u;
;             ATTN_DECODE(un, hn, Q0n, tbn) ATTN_FETCH(hn, Q0n, tbn); }
	v_lshl_add_u64 v[2:3], v[2:3], 0, 0
	v_lshl_add_u64 v[2:3], v[2:3], 0, v[0:1]
	v_cmp_lt_i32_e32 vcc, s4, v166
	global_load_dwordx4 v[106:109], v[2:3], off
	s_movk_i32 s4, 0xe00
	v_cndmask_b32_e32 v2, 0, v196, vcc
	v_add3_u32 v2, v166, v2, s4
	v_ashrrev_i32_e32 v2, 3, v2
	v_add_u32_e32 v2, s5, v2
	v_max_i32_e32 v2, 0, v2
	v_mov_b32_e32 v3, v1
	v_lshlrev_b64 v[2:3], 0, v[2:3]
	v_lshl_add_u64 v[2:3], v[2:3], 0, s[100:101]
	v_cndmask_b32_e32 v5, v6, v7, vcc
	v_cndmask_b32_e32 v4, v8, v9, vcc
	v_lshlrev_b64 v[2:3], 7, v[2:3]
	v_lshl_add_u64 v[2:3], v[4:5], 0, v[2:3]
	v_lshl_add_u64 v[2:3], v[2:3], 0, 0
	s_movk_i32 s4, 0xfbff
	v_lshl_add_u64 v[2:3], v[2:3], 0, v[0:1]
	v_cmp_lt_i32_e32 vcc, s4, v166
	global_load_dwordx4 v[110:113], v[2:3], off
	v_mov_b32_e32 v3, v1
	v_cndmask_b32_e32 v2, 0, v196, vcc
	v_add3_u32 v2, v166, v2, s72
	v_ashrrev_i32_e32 v2, 3, v2
	v_add_u32_e32 v2, s5, v2
	v_max_i32_e32 v2, 0, v2
	v_lshlrev_b64 v[2:3], 0, v[2:3]
	v_lshl_add_u64 v[2:3], v[2:3], 0, s[100:101]
	v_cndmask_b32_e32 v5, v6, v7, vcc
	v_cndmask_b32_e32 v4, v8, v9, vcc
	v_lshlrev_b64 v[2:3], 7, v[2:3]
	v_lshl_add_u64 v[2:3], v[4:5], 0, v[2:3]
	v_lshl_add_u64 v[2:3], v[2:3], 0, 0
	s_movk_i32 s4, 0xf9ff
	v_lshl_add_u64 v[2:3], v[2:3], 0, v[0:1]
	v_cmp_lt_i32_e32 vcc, s4, v166
	global_load_dwordx4 v[114:117], v[2:3], off
	s_movk_i32 s4, 0x1200
	v_cndmask_b32_e32 v2, 0, v196, vcc
	v_add3_u32 v2, v166, v2, s4
	v_ashrrev_i32_e32 v2, 3, v2
	v_add_u32_e32 v2, s5, v2
	v_max_i32_e32 v2, 0, v2
	v_mov_b32_e32 v3, v1
	v_lshlrev_b64 v[2:3], 0, v[2:3]
	v_lshl_add_u64 v[2:3], v[2:3], 0, s[100:101]
	v_cndmask_b32_e32 v5, v6, v7, vcc
	v_cndmask_b32_e32 v4, v8, v9, vcc
	v_lshlrev_b64 v[2:3], 7, v[2:3]
	v_lshl_add_u64 v[2:3], v[4:5], 0, v[2:3]
	v_lshl_add_u64 v[2:3], v[2:3], 0, 0
	s_movk_i32 s4, 0xf7ff
	v_lshl_add_u64 v[2:3], v[2:3], 0, v[0:1]
	v_cmp_lt_i32_e32 vcc, s4, v166
	global_load_dwordx4 v[118:121], v[2:3], off
	s_movk_i32 s4, 0x1400
	v_cndmask_b32_e32 v2, 0, v196, vcc
	v_add3_u32 v2, v166, v2, s4
	v_ashrrev_i32_e32 v2, 3, v2
	v_add_u32_e32 v2, s5, v2
	v_max_i32_e32 v2, 0, v2
	v_mov_b32_e32 v3, v1
	v_lshlrev_b64 v[2:3], 0, v[2:3]
	v_lshl_add_u64 v[2:3], v[2:3], 0, s[100:101]
	v_cndmask_b32_e32 v5, v6, v7, vcc
	v_cndmask_b32_e32 v4, v8, v9, vcc
	v_lshlrev_b64 v[2:3], 7, v[2:3]
	v_lshl_add_u64 v[2:3], v[4:5], 0, v[2:3]
	v_lshl_add_u64 v[2:3], v[2:3], 0, 0
	s_movk_i32 s4, 0xf5ff
	v_lshl_add_u64 v[2:3], v[2:3], 0, v[0:1]
	v_cmp_lt_i32_e32 vcc, s4, v166
	global_load_dwordx4 v[122:125], v[2:3], off
	s_movk_i32 s4, 0x1600
	v_cndmask_b32_e32 v2, 0, v196, vcc
	v_add3_u32 v2, v166, v2, s4
	v_ashrrev_i32_e32 v2, 3, v2
	v_add_u32_e32 v2, s5, v2
	v_max_i32_e32 v2, 0, v2
	v_mov_b32_e32 v3, v1
	v_lshlrev_b64 v[2:3], 0, v[2:3]
	v_lshl_add_u64 v[2:3], v[2:3], 0, s[100:101]
	v_cndmask_b32_e32 v5, v6, v7, vcc
	v_cndmask_b32_e32 v4, v8, v9, vcc
	v_lshlrev_b64 v[2:3], 7, v[2:3]
	v_lshl_add_u64 v[2:3], v[4:5], 0, v[2:3]
	v_lshl_add_u64 v[2:3], v[2:3], 0, 0
	v_lshl_add_u64 v[2:3], v[2:3], 0, v[0:1]
	global_load_dwordx4 v[126:129], v[2:3], off
	s_mov_b32 s4, s6
	v_writelane_b32 v250, s4, 13
	s_nop 1
	v_writelane_b32 v250, s5, 14
.LBB0_138:
	s_and_b64 vcc, exec, s[38:39]
	s_cbranch_vccnz .LBB0_187
	v_readlane_b32 s4, v250, 56
	v_readlane_b32 s5, v250, 57
	s_and_b64 s[4:5], s[4:5], exec
	v_readlane_b32 s4, v251, 0
	v_readlane_b32 s5, v251, 1
	s_cselect_b32 s69, s5, s83
	s_cselect_b32 s68, s4, s82
	s_add_u32 s86, s34, 0x400000
	s_addc_u32 s87, s35, 0
	s_ashr_i32 s2, s2, 6
	s_mul_i32 s4, s2, 0x1100
	s_add_i32 s15, s4, 0
	s_lshl_b32 s14, s2, 5
	s_add_i32 s15, s15, 0x1b000
	s_cmp_gt_i32 s2, 3
	s_cselect_b64 s[90:91], -1, 0
	s_cmp_gt_i32 s2, 2
	s_cselect_b64 s[88:89], -1, 0
	s_add_i32 s26, s14, 32
	s_cmp_gt_i32 s2, 1
	s_cselect_b64 s[4:5], -1, 0
	s_add_i32 s27, s14, 64
	v_readlane_b32 s6, v251, 2
	s_cmp_gt_i32 s2, 0
	s_cselect_b64 s[12:13], -1, 0
	s_add_i32 s6, s14, 0x60
	v_readlane_b32 s7, v251, 3
	s_cmp_gt_i32 s2, -1
	s_mov_b32 s65, s80
	s_mov_b32 s61, s79
	s_cselect_b64 s[16:17], -1, 0
	s_add_i32 s7, s14, 0x80
	s_mov_b32 s60, s78
	s_mov_b32 s2, s78
	s_lshr_b32 vcc_lo, s78, 4
	s_and_b32 vcc_lo, vcc_lo, s31
	s_lshl_b32 vcc_lo, vcc_lo, 8
	s_add_i32 vcc_lo, vcc_lo, s14
	v_and_b32_e32 v252, 31, v166
	v_or_b32_e32 v252, vcc_lo, v252
	v_mov_b32_e32 v253, 0
	v_lshl_add_u64 v[252:253], v[252:253], 0, s[100:101]
	v_lshlrev_b64 v[252:253], 7, v[252:253]
	v_lshl_add_u64 v[252:253], s[68:69], 0, v[252:253]
	v_bfe_u32 v254, v166, 5, 1
	v_lshlrev_b32_e32 v254, 4, v254
	v_mov_b32_e32 v255, 0
	v_lshl_add_u64 v[252:253], v[252:253], 0, v[254:255]
	global_load_dwordx4 v[232:235], v[252:253], off
	global_load_dwordx4 v[236:239], v[252:253], off offset:32
	global_load_dwordx4 v[240:243], v[252:253], off offset:64
	global_load_dwordx4 v[244:247], v[252:253], off offset:96
	s_branch .LBB0_141
.LBB0_140:
	s_or_b64 exec, exec, s[36:37]
	s_waitcnt lgkmcnt(0)
	s_barrier
	s_waitcnt vmcnt(4)
	v_mov_b64_e32 v[132:133], v[16:17]
	v_mov_b64_e32 v[136:137], v[12:13]
	v_mov_b64_e32 v[140:141], v[8:9]
	v_mov_b64_e32 v[144:145], v[4:5]
	s_andn2_b64 vcc, exec, s[20:21]
	v_mov_b64_e32 v[130:131], v[14:15]
	v_mov_b64_e32 v[134:135], v[10:11]
	v_mov_b64_e32 v[138:139], v[6:7]
	v_mov_b64_e32 v[142:143], v[2:3]
	s_cbranch_vccz .LBB0_186
	s_branch .Lmy_attn_top

; #define GAS __attribute__((address_space(1)))
; #define LAS __attribute__((address_space(3)))
; __device__ __forceinline__ void attn_phase(LAS unsigned char* lds, const bf16* Qg, const bf16* Kg, const bf16* Vg  , bf16* OB, float* LSE, int g, int dsh, int u_lo, int u_hi) {
;     ...
;     for (int u = u_lo + blockIdx.x; u < u_hi; u += gridDim.x) {
;         int tq_ = tid; asm volatile("" : "+v"(tq_));
;         { const int tid = tq_, lane = tid & 63, r = lane & 31, hh = lane >> 5;
;         ATTN_DECODE(u, h, Q0, tokbase)
; #pragma unroll
;         for (int it = 0; it < 12; ++it) { const int piece = tid + 512 * it; const int kv = piece >= 3072 ? 1 : 0; const int pr = piece - 3072 * kv; const int row = pr >> 3, ch = pr & 7;
;             const bool live = (Q0 - 128 + row) >= 0; v4u val = kvr[it]; if (!live) val = (v4u){0u, 0u, 0u, 0u};
;             *(LAS v4u*)((kv ? Vl : Kl) + row * AT_PITCH + ch * 16) = val; }
;         const int qpos = Q0 + 32 * wave + r; const size_t qtok = tokbase + (size_t)qpos * dil;
;         bf16x8 qf[4];
; #pragma unroll
;         for (int ks = 0; ks < 4; ++ks) qf[ks] = *(const GAS bf16x8*)(Qg + qtok * 1024 + h * 64 + 16 * ks + 8 * hh);
.Lmy_attn_top:
	v_mov_b64_e32 v[158:159], v[232:233]
	v_mov_b64_e32 v[160:161], v[234:235]
	v_mov_b64_e32 v[154:155], v[236:237]
	v_mov_b64_e32 v[156:157], v[238:239]
	v_mov_b64_e32 v[150:151], v[240:241]
	v_mov_b64_e32 v[152:153], v[242:243]
	v_mov_b64_e32 v[146:147], v[244:245]
	v_mov_b64_e32 v[148:149], v[246:247]
	v_mov_b32_e32 v167, v166
	s_movk_i32 s23, 0xbff
	s_mov_b32 s36, s2
	s_ashr_i32 s2, s2, 4
	v_lshlrev_b32_e32 v0, 4, v167
	v_cmp_lt_i32_e64 s[40:41], s23, v167
	s_and_b32 s79, s2, s31
	v_and_b32_e32 v2, 0x70, v0
	v_cndmask_b32_e64 v0, 0, v196, s[40:41]
	s_lshl_b32 s78, s79, 8
	v_add_u32_e32 v0, v0, v167
	v_readlane_b32 s23, v250, 15
	s_sub_i32 s37, 0x7f, s78
	v_ashrrev_i32_e32 v3, 3, v0
	v_mov_b32_e32 v0, s23
	v_cmp_lt_i32_e32 vcc, s37, v3
	v_cndmask_b32_e64 v8, 0, v0, s[40:41]
	v_mul_lo_u32 v9, v3, s97
	s_movk_i32 s23, 0x9ff
	v_cndmask_b32_e32 v7, 0, v85, vcc
	v_cndmask_b32_e32 v6, 0, v84, vcc
	v_cndmask_b32_e32 v5, 0, v83, vcc
	v_cndmask_b32_e32 v4, 0, v82, vcc
	v_add3_u32 v8, v8, v9, v2
	v_cmp_lt_i32_e32 vcc, s23, v167
	ds_write_b128 v8, v[4:7]
	s_movk_i32 s23, 0x7ff
	v_cndmask_b32_e32 v4, 0, v196, vcc
	v_add3_u32 v4, v167, v4, s64
	v_ashrrev_i32_e32 v8, 3, v4
	v_cmp_lt_i32_e64 s[38:39], s37, v8
	v_cndmask_b32_e32 v9, 0, v0, vcc
	v_mul_lo_u32 v10, v8, s97
	v_cndmask_b32_e64 v7, 0, v89, s[38:39]
	v_cndmask_b32_e64 v6, 0, v88, s[38:39]
	v_cndmask_b32_e64 v5, 0, v87, s[38:39]
	v_cndmask_b32_e64 v4, 0, v86, s[38:39]
	v_add3_u32 v9, v9, v10, v2
	v_cmp_lt_i32_e64 s[38:39], s23, v167
	ds_write_b128 v9, v[4:7]
	s_movk_i32 s23, 0x400
	v_cndmask_b32_e64 v4, 0, v196, s[38:39]
	v_add3_u32 v4, v167, v4, s23
	v_ashrrev_i32_e32 v9, 3, v4
	v_cmp_lt_i32_e64 s[42:43], s37, v9
	v_cndmask_b32_e64 v10, 0, v0, s[38:39]
	v_mul_lo_u32 v11, v9, s97
	s_movk_i32 s23, 0x5ff
	v_cndmask_b32_e64 v7, 0, v93, s[42:43]
	v_cndmask_b32_e64 v6, 0, v92, s[42:43]
	v_cndmask_b32_e64 v5, 0, v91, s[42:43]
	v_cndmask_b32_e64 v4, 0, v90, s[42:43]
	v_add3_u32 v10, v10, v11, v2
	v_cmp_lt_i32_e64 s[42:43], s23, v167
	ds_write_b128 v10, v[4:7]
	s_movk_i32 s23, 0x600
	v_cndmask_b32_e64 v4, 0, v196, s[42:43]
	v_add3_u32 v4, v167, v4, s23
	v_ashrrev_i32_e32 v10, 3, v4
	v_cmp_lt_i32_e64 s[44:45], s37, v10
	v_cndmask_b32_e64 v11, 0, v0, s[42:43]
	v_mul_lo_u32 v12, v10, s97
	s_movk_i32 s23, 0x3ff
	v_cndmask_b32_e64 v7, 0, v97, s[44:45]
	v_cndmask_b32_e64 v6, 0, v96, s[44:45]
	v_cndmask_b32_e64 v5, 0, v95, s[44:45]
	v_cndmask_b32_e64 v4, 0, v94, s[44:45]
	v_add3_u32 v11, v11, v12, v2
	v_cmp_lt_i32_e64 s[44:45], s23, v167
	ds_write_b128 v11, v[4:7]
	s_movk_i32 s23, 0x800
	v_cndmask_b32_e64 v4, 0, v196, s[44:45]
	v_add3_u32 v4, v167, v4, s23
	v_ashrrev_i32_e32 v11, 3, v4
	v_cmp_lt_i32_e64 s[46:47], s37, v11
	v_cndmask_b32_e64 v12, 0, v0, s[44:45]
	v_mul_lo_u32 v13, v11, s97
	s_movk_i32 s23, 0x1ff
	v_cndmask_b32_e64 v7, 0, v101, s[46:47]
	v_cndmask_b32_e64 v6, 0, v100, s[46:47]
	v_cndmask_b32_e64 v5, 0, v99, s[46:47]
	v_cndmask_b32_e64 v4, 0, v98, s[46:47]
	v_add3_u32 v12, v12, v13, v2
	v_cmp_lt_i32_e64 s[46:47], s23, v167
	ds_write_b128 v12, v[4:7]
	s_movk_i32 s23, 0xa00
	v_cndmask_b32_e64 v4, 0, v196, s[46:47]
	v_add3_u32 v4, v167, v4, s23
	v_ashrrev_i32_e32 v12, 3, v4
	v_cmp_lt_i32_e64 s[48:49], s37, v12
	v_cndmask_b32_e64 v13, 0, v0, s[46:47]
	v_mul_lo_u32 v14, v12, s97
	v_cndmask_b32_e64 v7, 0, v105, s[48:49]
	v_cndmask_b32_e64 v6, 0, v104, s[48:49]
	v_cndmask_b32_e64 v5, 0, v103, s[48:49]
	v_cndmask_b32_e64 v4, 0, v102, s[48:49]
	v_add3_u32 v13, v13, v14, v2
	ds_write_b128 v13, v[4:7]
	v_add_u32_e32 v4, 0xc00, v167
	v_cmp_lt_i32_e64 s[48:49], -1, v167
	s_movk_i32 s23, 0xfdff
	s_ashr_i32 s20, s36, 8
	v_cndmask_b32_e64 v4, v4, v167, s[48:49]
	v_ashrrev_i32_e32 v13, 3, v4
	v_cmp_lt_i32_e64 s[50:51], s37, v13
	v_cndmask_b32_e64 v14, 0, v0, s[48:49]
	v_mul_lo_u32 v15, v13, s97
	v_cndmask_b32_e64 v7, 0, v109, s[50:51]
	v_cndmask_b32_e64 v6, 0, v108, s[50:51]
	v_cndmask_b32_e64 v5, 0, v107, s[50:51]
	v_cndmask_b32_e64 v4, 0, v106, s[50:51]
	v_add3_u32 v14, v14, v15, v2
	v_cmp_lt_i32_e64 s[50:51], s23, v167
	ds_write_b128 v14, v[4:7]
	s_movk_i32 s23, 0xe00
	v_cndmask_b32_e64 v4, 0, v196, s[50:51]
	v_add3_u32 v4, v167, v4, s23
	v_ashrrev_i32_e32 v14, 3, v4
	v_cmp_lt_i32_e64 s[52:53], s37, v14
	v_cndmask_b32_e64 v15, 0, v0, s[50:51]
	v_mul_lo_u32 v16, v14, s97
	s_movk_i32 s23, 0xfbff
	v_cndmask_b32_e64 v7, 0, v113, s[52:53]
	v_cndmask_b32_e64 v6, 0, v112, s[52:53]
	v_cndmask_b32_e64 v5, 0, v111, s[52:53]
	v_cndmask_b32_e64 v4, 0, v110, s[52:53]
	v_add3_u32 v15, v15, v16, v2
	v_cmp_lt_i32_e64 s[52:53], s23, v167
	ds_write_b128 v15, v[4:7]
	s_movk_i32 s23, 0xf9ff
	v_cndmask_b32_e64 v4, 0, v196, s[52:53]
	v_add3_u32 v4, v167, v4, s72
	v_ashrrev_i32_e32 v15, 3, v4
	v_cmp_lt_i32_e64 s[54:55], s37, v15
	v_cndmask_b32_e64 v16, 0, v0, s[52:53]
	v_mul_lo_u32 v17, v15, s97
	v_cndmask_b32_e64 v7, 0, v117, s[54:55]
	v_cndmask_b32_e64 v6, 0, v116, s[54:55]
	v_cndmask_b32_e64 v5, 0, v115, s[54:55]
	v_cndmask_b32_e64 v4, 0, v114, s[54:55]
	v_add3_u32 v16, v16, v17, v2
	v_cmp_lt_i32_e64 s[54:55], s23, v167
	ds_write_b128 v16, v[4:7]
	s_movk_i32 s23, 0x1200
	v_cndmask_b32_e64 v4, 0, v196, s[54:55]
	v_add3_u32 v4, v167, v4, s23
	v_ashrrev_i32_e32 v16, 3, v4
	v_cmp_lt_i32_e64 s[56:57], s37, v16
	v_cndmask_b32_e64 v17, 0, v0, s[54:55]
	v_mul_lo_u32 v18, v16, s97
	s_movk_i32 s23, 0xf7ff
	v_cndmask_b32_e64 v7, 0, v121, s[56:57]
	v_cndmask_b32_e64 v6, 0, v120, s[56:57]
	v_cndmask_b32_e64 v5, 0, v119, s[56:57]
	v_cndmask_b32_e64 v4, 0, v118, s[56:57]
	v_add3_u32 v17, v17, v18, v2
	v_cmp_lt_i32_e64 s[56:57], s23, v167
	ds_write_b128 v17, v[4:7]
	s_movk_i32 s23, 0x1400
	v_cndmask_b32_e64 v4, 0, v196, s[56:57]
; #define GAS __attribute__((address_space(1)))
; #define LAS __attribute__((address_space(3)))
; #define LDS_BAR() do { asm volatile("s_waitcnt lgkmcnt(0)" ::: "memory"); __builtin_amdgcn_s_barrier(); asm volatile("" ::: "memory"); } while (0)
; __device__ __forceinline__ void attn_phase(LAS unsigned char* lds, const bf16* Qg, const bf16* Kg, const bf16* Vg  , bf16* OB, float* LSE, int g, int dsh, int u_lo, int u_hi) {
;     ...
;         for (int it = 0; it < 12; ++it) { const int piece = tid + 512 * it; const int kv = piece >= 3072 ? 1 : 0; const int pr = piece - 3072 * kv; const int row = pr >> 3, ch = pr & 7;
;             const bool live = (Q0 - 128 + row) >= 0; v4u val = kvr[it]; if (!live) val = (v4u){0u, 0u, 0u, 0u};
;             *(LAS v4u*)((kv ? Vl : Kl) + row * AT_PITCH + ch * 16) = val; }
;         const int qpos = Q0 + 32 * wave + r; const size_t qtok = tokbase + (size_t)qpos * dil;
;         bf16x8 qf[4];
; #pragma unroll
;         for (int ks = 0; ks < 4; ++ks) qf[ks] = *(const GAS bf16x8*)(Qg + qtok * 1024 + h * 64 + 16 * ks + 8 * hh);
;         LDS_BAR();
;         { const int un0 = u + (int)gridDim.x; const int un = un0 < u_hi ? un0 : u;
;             ATTN_DECODE(un, hn, Q0n, tbn) ATTN_FETCH(hn, Q0n, tbn); }
;     ...
;         if (g > 0) {
; #pragma unroll
;             for (int j4 = 0; j4 < 4; ++j4) pv4[j4] = *(const GAS v4u*)(OB + (tokbase + (size_t)(Q0 + 32 * wave + rr0 + 8 * j4) * dil) * 1024 + h * 64 + cc * 8); }
	v_add3_u32 v4, v167, v4, s23
	v_ashrrev_i32_e32 v17, 3, v4
	v_cmp_lt_i32_e64 s[58:59], s37, v17
	v_cndmask_b32_e64 v18, 0, v0, s[56:57]
	v_mul_lo_u32 v19, v17, s97
	s_movk_i32 s23, 0xf5ff
	v_cndmask_b32_e64 v7, 0, v125, s[58:59]
	v_cndmask_b32_e64 v6, 0, v124, s[58:59]
	v_cndmask_b32_e64 v5, 0, v123, s[58:59]
	v_cndmask_b32_e64 v4, 0, v122, s[58:59]
	v_add3_u32 v18, v18, v19, v2
	v_cmp_lt_i32_e64 s[58:59], s23, v167
	ds_write_b128 v18, v[4:7]
	s_movk_i32 s23, 0x1600
	v_cndmask_b32_e64 v4, 0, v196, s[58:59]
	v_add3_u32 v4, v167, v4, s23
	s_ashr_i32 s2, s2, s22
	v_readlane_b32 s80, v250, 59
	s_ashr_i32 s21, s20, 31
	v_ashrrev_i32_e32 v18, 3, v4
	s_and_b32 s2, s2, s80
	v_cmp_lt_i32_e64 s[62:63], s37, v18
	s_and_b32 s77, s36, 15
	s_lshl_b64 s[20:21], s[20:21], 12
	v_cndmask_b32_e64 v7, 0, v129, s[62:63]
	v_cndmask_b32_e64 v6, 0, v128, s[62:63]
	v_cndmask_b32_e64 v5, 0, v127, s[62:63]
	v_cndmask_b32_e64 v4, 0, v126, s[62:63]
	v_cndmask_b32_e64 v0, 0, v0, s[58:59]
	v_mul_lo_u32 v19, v18, s97
	s_add_u32 s62, s20, s2
	v_add3_u32 v0, v0, v19, v2
	v_and_b32_e32 v169, 31, v167
	s_addc_u32 s63, s21, 0
	s_add_i32 s78, s78, s14
	ds_write_b128 v0, v[4:7]
	v_or_b32_e32 v4, s78, v169
	v_ashrrev_i32_e32 v5, 31, v4
	v_lshlrev_b64 v[4:5], s30, v[4:5]
	v_lshl_add_u64 v[164:165], v[4:5], 0, s[62:63]
	s_lshl_b32 s94, s77, 7
	s_add_i32 s2, s36, s66
	v_lshlrev_b64 v[4:5], 11, v[164:165]
	s_cmpk_gt_i32 s2, 0x7ff
	v_lshl_add_u64 v[4:5], s[68:69], 0, v[4:5]
	s_cselect_b64 s[20:21], -1, 0
	s_cmpk_lt_i32 s2, 0x800
	v_lshl_add_u64 v[4:5], v[4:5], 0, s[94:95]
	s_cselect_b32 s94, s2, s36
	s_ashr_i32 s36, s94, 4
	s_and_b32 s37, s36, s31
	s_ashr_i32 s36, s36, s22
	s_and_b32 s80, s36, s80
	s_ashr_i32 s36, s94, 8
	s_lshl_b32 s23, s37, 8
	s_ashr_i32 s37, s36, 31
	s_lshl_b64 s[36:37], s[36:37], 12
	v_bfe_u32 v168, v167, 5, 1
	s_add_u32 s36, s36, s80
	v_lshlrev_b32_e32 v0, 4, v168
	s_addc_u32 s37, s37, 0
	s_addk_i32 s23, 0xff80
	v_lshl_add_u64 v[4:5], v[4:5], 0, v[0:1]
	v_add_u32_e32 v3, s23, v3
	s_cmp_eq_u64 s[28:29], 0
	s_cbranch_scc1 .Lmy_attn_nopre
	v_lshlrev_b64 v[252:253], 6, v[164:165]
	v_lshl_add_u64 v[252:253], s[86:87], 0, v[252:253]
	s_lshl_b32 s100, s77, 2
	s_mov_b32 s101, 0
	v_lshl_add_u64 v[252:253], v[252:253], 0, s[100:101]
	global_load_dword v254, v[252:253], off
	s_lshl_b32 s100, s77, 7
	s_add_u32 s100, s18, s100
	s_addc_u32 s101, s19, 0
	v_and_b32_e32 v232, 63, v167
	v_and_b32_e32 v234, 7, v167
	v_lshrrev_b32_e32 v232, 3, v232
	v_lshlrev_b32_e32 v234, 4, v234
	v_mov_b32_e32 v235, 0
	v_or_b32_e32 v232, s78, v232
	v_mov_b32_e32 v233, 0
	v_lshl_add_u64 v[234:235], s[100:101], 0, v[234:235]
	v_lshlrev_b64 v[252:253], s30, v[232:233]
	v_lshl_add_u64 v[252:253], v[252:253], 0, s[62:63]
	v_lshlrev_b64 v[252:253], 11, v[252:253]
	v_lshl_add_u64 v[252:253], v[234:235], 0, v[252:253]
	global_load_dwordx4 v[216:219], v[252:253], off
	v_or_b32_e32 v232, 8, v232
	v_lshlrev_b64 v[252:253], s30, v[232:233]
	v_lshl_add_u64 v[252:253], v[252:253], 0, s[62:63]
	v_lshlrev_b64 v[252:253], 11, v[252:253]
	v_lshl_add_u64 v[252:253], v[234:235], 0, v[252:253]
	global_load_dwordx4 v[220:223], v[252:253], off
	v_xor_b32_e32 v232, 24, v232
	v_lshlrev_b64 v[252:253], s30, v[232:233]
	v_lshl_add_u64 v[252:253], v[252:253], 0, s[62:63]
	v_lshlrev_b64 v[252:253], 11, v[252:253]
	v_lshl_add_u64 v[252:253], v[234:235], 0, v[252:253]
	global_load_dwordx4 v[224:227], v[252:253], off
	v_or_b32_e32 v232, 8, v232
	v_lshlrev_b64 v[252:253], s30, v[232:233]
	v_lshl_add_u64 v[252:253], v[252:253], 0, s[62:63]
	v_lshlrev_b64 v[252:253], 11, v[252:253]
	v_lshl_add_u64 v[252:253], v[234:235], 0, v[252:253]
	global_load_dwordx4 v[228:231], v[252:253], off
.Lmy_attn_nopre:
	s_and_b32 s101, s36, 0xfff
	s_lshl_b32 s101, s101, 12
	s_lshr_b32 s101, s101, s30
	s_andn2_b32 s100, s36, 0xfff
	s_lshl_b32 s100, s100, 4
	s_add_i32 s100, s100, s101
	s_and_b32 s101, s94, 15
	s_lshl_b32 s101, s101, 12
	s_add_i32 s100, s100, s101
	s_mov_b32 s101, 0
	v_max_i32_e32 v4, 0, v3
	v_mov_b32_e32 v5, v1
	v_lshlrev_b64 v[4:5], 0, v[4:5]
	v_mov_b32_e32 v19, s8
	v_mov_b32_e32 v20, s11
	v_mov_b32_e32 v21, s9
	v_mov_b32_e32 v22, s10
	v_lshl_add_u64 v[4:5], v[4:5], 0, s[100:101]
	v_cndmask_b32_e64 v7, v19, v20, s[40:41]
	v_cndmask_b32_e64 v6, v21, v22, s[40:41]
	v_lshlrev_b64 v[4:5], 7, v[4:5]
	s_lshl_b32 s40, s94, 7
	v_lshl_add_u64 v[4:5], v[6:7], 0, v[4:5]
	s_and_b32 s94, s40, 0x780
	v_lshl_add_u64 v[4:5], v[4:5], 0, 0
	v_mov_b32_e32 v3, v1
	s_waitcnt lgkmcnt(0)
	s_barrier
; #define GAS __attribute__((address_space(1)))
; #define LAS __attribute__((address_space(3)))
; #define LDS_BAR() do { asm volatile("s_waitcnt lgkmcnt(0)" ::: "memory"); __builtin_amdgcn_s_barrier(); asm volatile("" ::: "memory"); } while (0)
; #define MFMA32(a, b, c) __builtin_amdgcn_mfma_f32_32x32x16_bf16((a), (b), (c), 0, 0, 0)
; __device__ __forceinline__ void attn_phase(LAS unsigned char* lds, const bf16* Qg, const bf16* Kg, const bf16* Vg  , bf16* OB, float* LSE, int g, int dsh, int u_lo, int u_hi) {
;     ...
;     if (u_lo + (int)blockIdx.x < u_hi) { ATTN_DECODE(u_lo + (int)blockIdx.x, h0, Q00, tb0) ATTN_FETCH(h0, Q00, tb0); }
;     for (int u = u_lo + blockIdx.x; u < u_hi; u += gridDim.x) {
;         int tq_ = tid; asm volatile("" : "+v"(tq_));
;         { const int tid = tq_, lane = tid & 63, r = lane & 31, hh = lane >> 5;
;         ATTN_DECODE(u, h, Q0, tokbase)
; #pragma unroll
;         for (int it = 0; it < 12; ++it) { const int piece = tid + 512 * it; const int kv = piece >= 3072 ? 1 : 0; const int pr = piece - 3072 * kv; const int row = pr >> 3, ch = pr & 7;
;             const bool live = (Q0 - 128 + row) >= 0; v4u val = kvr[it]; if (!live) val = (v4u){0u, 0u, 0u, 0u};
;             *(LAS v4u*)((kv ? Vl : Kl) + row * AT_PITCH + ch * 16) = val; }
;         const int qpos = Q0 + 32 * wave + r; const size_t qtok = tokbase + (size_t)qpos * dil;
;         bf16x8 qf[4];
; #pragma unroll
;         for (int ks = 0; ks < 4; ++ks) qf[ks] = *(const GAS bf16x8*)(Qg + qtok * 1024 + h * 64 + 16 * ks + 8 * hh);
;         LDS_BAR();
;         { const int un0 = u + (int)gridDim.x; const int un = un0 < u_hi ? un0 : u;
;             ATTN_DECODE(un, hn, Q0n, tbn) ATTN_FETCH(hn, Q0n, tbn); }
;     ...
;         for (int c = 0; c < 5; ++c) {
; #pragma unroll
;             for (int i = 0; i < 16; ++i) st[c][i] = 0.f;
;             if (!(first && (wave + c < 4)))
; #pragma unroll
;             for (int ks = 0; ks < 4; ++ks) { const bf16x8 kf = *(const LAS bf16x8*)(Kl + (32 * (wave + c) + r) * AT_PITCH + (16 * ks + 8 * hh) * 2); st[c] = MFMA32(kf, qf[ks], st[c]); } }
	v_add_u32_e32 v252, s23, v169
	v_add_u32_e32 v252, s14, v252
	v_add_u32_e32 v252, 0x80, v252
	v_mov_b32_e32 v253, 0
	v_lshl_add_u64 v[252:253], v[252:253], 0, s[100:101]
	v_lshlrev_b64 v[252:253], 7, v[252:253]
	v_lshl_add_u64 v[252:253], s[68:69], 0, v[252:253]
	v_lshl_add_u64 v[252:253], v[252:253], 0, v[0:1]
	global_load_dwordx4 v[232:235], v[252:253], off
	global_load_dwordx4 v[236:239], v[252:253], off offset:32
	global_load_dwordx4 v[240:243], v[252:253], off offset:64
	global_load_dwordx4 v[244:247], v[252:253], off offset:96
	v_lshl_add_u64 v[4:5], v[4:5], 0, v[2:3]
	global_load_dwordx4 v[82:85], v[4:5], off
	v_add_u32_e32 v4, s23, v8
	v_max_i32_e32 v4, 0, v4
	v_mov_b32_e32 v5, v1
	v_lshlrev_b64 v[4:5], 0, v[4:5]
	v_lshl_add_u64 v[4:5], v[4:5], 0, s[100:101]
	v_cndmask_b32_e32 v7, v19, v20, vcc
	v_cndmask_b32_e32 v6, v21, v22, vcc
	v_lshlrev_b64 v[4:5], 7, v[4:5]
	v_lshl_add_u64 v[4:5], v[6:7], 0, v[4:5]
	v_lshl_add_u64 v[4:5], v[4:5], 0, 0
	v_lshl_add_u64 v[4:5], v[4:5], 0, v[2:3]
	global_load_dwordx4 v[86:89], v[4:5], off
	v_add_u32_e32 v4, s23, v9
	v_max_i32_e32 v4, 0, v4
	v_mov_b32_e32 v5, v1
	v_lshlrev_b64 v[4:5], 0, v[4:5]
	v_lshl_add_u64 v[4:5], v[4:5], 0, s[100:101]
	v_cndmask_b32_e64 v7, v19, v20, s[38:39]
	v_cndmask_b32_e64 v6, v21, v22, s[38:39]
	v_lshlrev_b64 v[4:5], 7, v[4:5]
	v_lshl_add_u64 v[4:5], v[6:7], 0, v[4:5]
	v_lshl_add_u64 v[4:5], v[4:5], 0, 0
	v_lshl_add_u64 v[4:5], v[4:5], 0, v[2:3]
	global_load_dwordx4 v[90:93], v[4:5], off
	v_add_u32_e32 v4, s23, v10
	v_max_i32_e32 v4, 0, v4
	v_mov_b32_e32 v5, v1
	v_lshlrev_b64 v[4:5], 0, v[4:5]
	v_lshl_add_u64 v[4:5], v[4:5], 0, s[100:101]
	v_cndmask_b32_e64 v7, v19, v20, s[42:43]
	v_cndmask_b32_e64 v6, v21, v22, s[42:43]
	v_lshlrev_b64 v[4:5], 7, v[4:5]
	v_lshl_add_u64 v[4:5], v[6:7], 0, v[4:5]
	v_lshl_add_u64 v[4:5], v[4:5], 0, 0
	v_lshl_add_u64 v[4:5], v[4:5], 0, v[2:3]
	global_load_dwordx4 v[94:97], v[4:5], off
	v_add_u32_e32 v4, s23, v11
	v_max_i32_e32 v4, 0, v4
	v_mov_b32_e32 v5, v1
	v_lshlrev_b64 v[4:5], 0, v[4:5]
	v_lshl_add_u64 v[4:5], v[4:5], 0, s[100:101]
	v_cndmask_b32_e64 v7, v19, v20, s[44:45]
	v_cndmask_b32_e64 v6, v21, v22, s[44:45]
	v_lshlrev_b64 v[4:5], 7, v[4:5]
	v_lshl_add_u64 v[4:5], v[6:7], 0, v[4:5]
	v_lshl_add_u64 v[4:5], v[4:5], 0, 0
	v_lshl_add_u64 v[4:5], v[4:5], 0, v[2:3]
	global_load_dwordx4 v[98:101], v[4:5], off
	v_add_u32_e32 v4, s23, v12
	v_max_i32_e32 v4, 0, v4
	v_mov_b32_e32 v5, v1
	v_lshlrev_b64 v[4:5], 0, v[4:5]
	v_lshl_add_u64 v[4:5], v[4:5], 0, s[100:101]
	v_cndmask_b32_e64 v7, v19, v20, s[46:47]
	v_cndmask_b32_e64 v6, v21, v22, s[46:47]
	v_lshlrev_b64 v[4:5], 7, v[4:5]
	v_lshl_add_u64 v[4:5], v[6:7], 0, v[4:5]
	v_lshl_add_u64 v[4:5], v[4:5], 0, 0
	v_lshl_add_u64 v[4:5], v[4:5], 0, v[2:3]
	global_load_dwordx4 v[102:105], v[4:5], off
	v_add_u32_e32 v4, s23, v13
	v_max_i32_e32 v4, 0, v4
	v_mov_b32_e32 v5, v1
	v_lshlrev_b64 v[4:5], 0, v[4:5]
	v_lshl_add_u64 v[4:5], v[4:5], 0, s[100:101]
	v_cndmask_b32_e64 v7, v19, v20, s[48:49]
	v_cndmask_b32_e64 v6, v21, v22, s[48:49]
	v_lshlrev_b64 v[4:5], 7, v[4:5]
	v_lshl_add_u64 v[4:5], v[6:7], 0, v[4:5]
	v_lshl_add_u64 v[4:5], v[4:5], 0, 0
	v_lshl_add_u64 v[4:5], v[4:5], 0, v[2:3]
	global_load_dwordx4 v[106:109], v[4:5], off
	v_add_u32_e32 v4, s23, v14
	v_max_i32_e32 v4, 0, v4
	v_mov_b32_e32 v5, v1
	v_lshlrev_b64 v[4:5], 0, v[4:5]
	v_lshl_add_u64 v[4:5], v[4:5], 0, s[100:101]
	v_cndmask_b32_e64 v7, v19, v20, s[50:51]
	v_cndmask_b32_e64 v6, v21, v22, s[50:51]
	v_lshlrev_b64 v[4:5], 7, v[4:5]
	v_lshl_add_u64 v[4:5], v[6:7], 0, v[4:5]
	v_lshl_add_u64 v[4:5], v[4:5], 0, 0
	v_lshl_add_u64 v[4:5], v[4:5], 0, v[2:3]
	global_load_dwordx4 v[110:113], v[4:5], off
	v_add_u32_e32 v4, s23, v15
	v_max_i32_e32 v4, 0, v4
	v_mov_b32_e32 v5, v1
	v_lshlrev_b64 v[4:5], 0, v[4:5]
	v_lshl_add_u64 v[4:5], v[4:5], 0, s[100:101]
	v_cndmask_b32_e64 v7, v19, v20, s[52:53]
	v_cndmask_b32_e64 v6, v21, v22, s[52:53]
	v_lshlrev_b64 v[4:5], 7, v[4:5]
	v_lshl_add_u64 v[4:5], v[6:7], 0, v[4:5]
	v_lshl_add_u64 v[4:5], v[4:5], 0, 0
	v_lshl_add_u64 v[4:5], v[4:5], 0, v[2:3]
	global_load_dwordx4 v[114:117], v[4:5], off
	v_add_u32_e32 v4, s23, v16
	v_max_i32_e32 v4, 0, v4
	v_mov_b32_e32 v5, v1
	v_lshlrev_b64 v[4:5], 0, v[4:5]
	v_lshl_add_u64 v[4:5], v[4:5], 0, s[100:101]
	v_cndmask_b32_e64 v7, v19, v20, s[54:55]
	v_cndmask_b32_e64 v6, v21, v22, s[54:55]
	v_lshlrev_b64 v[4:5], 7, v[4:5]
	v_lshl_add_u64 v[4:5], v[6:7], 0, v[4:5]
	v_lshl_add_u64 v[4:5], v[4:5], 0, 0
	v_lshl_add_u64 v[4:5], v[4:5], 0, v[2:3]
	global_load_dwordx4 v[118:121], v[4:5], off
	v_add_u32_e32 v4, s23, v17
	v_max_i32_e32 v4, 0, v4
	v_mov_b32_e32 v5, v1
	v_lshlrev_b64 v[4:5], 0, v[4:5]
	v_lshl_add_u64 v[4:5], v[4:5], 0, s[100:101]
	v_cndmask_b32_e64 v7, v19, v20, s[56:57]
	v_cndmask_b32_e64 v6, v21, v22, s[56:57]
	v_lshlrev_b64 v[4:5], 7, v[4:5]
	v_lshl_add_u64 v[4:5], v[6:7], 0, v[4:5]
	v_lshl_add_u64 v[4:5], v[4:5], 0, 0
	v_lshl_add_u64 v[4:5], v[4:5], 0, v[2:3]
	global_load_dwordx4 v[122:125], v[4:5], off
	v_add_u32_e32 v4, s23, v18
	v_max_i32_e32 v4, 0, v4
	v_mov_b32_e32 v5, v1
	v_lshlrev_b64 v[4:5], 0, v[4:5]
	v_lshl_add_u64 v[4:5], v[4:5], 0, s[100:101]
	v_cndmask_b32_e64 v7, v19, v20, s[58:59]
	v_cndmask_b32_e64 v6, v21, v22, s[58:59]
	v_lshlrev_b64 v[4:5], 7, v[4:5]
	v_lshl_add_u64 v[4:5], v[6:7], 0, v[4:5]
	v_lshl_add_u64 v[4:5], v[4:5], 0, 0
	v_lshl_add_u64 v[2:3], v[4:5], 0, v[2:3]
	global_load_dwordx4 v[126:129], v[2:3], off
	s_cmp_lg_u32 s79, 0
	s_cselect_b64 s[38:39], -1, 0
	s_or_b64 s[54:55], s[38:39], s[90:91]
	v_cndmask_b32_e64 v3, 0, 1, s[54:55]
	v_add_u32_e32 v0, 0, v0
	v_mov_b32_e32 v2, 0
	v_cmp_ne_u32_e64 s[46:47], 1, v3
	s_andn2_b64 vcc, exec, s[54:55]
	v_mov_b32_e32 v18, 0
	v_mov_b32_e32 v19, 0
	v_mov_b32_e32 v20, 0
	v_mov_b32_e32 v21, 0
	v_mov_b32_e32 v22, 0
	v_mov_b32_e32 v23, 0
	v_mov_b32_e32 v24, 0
	v_mov_b32_e32 v25, 0
	v_mov_b32_e32 v26, 0
	v_mov_b32_e32 v27, 0
	v_mov_b32_e32 v28, 0
	v_mov_b32_e32 v29, 0
	v_mov_b32_e32 v30, 0
	v_mov_b32_e32 v31, 0
	v_mov_b32_e32 v32, 0
	v_mov_b32_e32 v33, 0
	s_cbranch_vccnz .LBB0_143
	v_or_b32_e32 v3, s14, v169
	v_mad_u64_u32 v[8:9], s[36:37], v3, s97, v[0:1]
	ds_read_b128 v[4:7], v8
	s_waitcnt lgkmcnt(0)
	v_mfma_f32_32x32x16_bf16 v[18:33], v[4:7], v[158:161], 0
	ds_read_b128 v[4:7], v8 offset:32
	s_waitcnt lgkmcnt(0)
	v_mfma_f32_32x32x16_bf16 v[18:33], v[4:7], v[154:157], v[18:33]
	ds_read_b128 v[4:7], v8 offset:64
	s_waitcnt lgkmcnt(0)
	v_mfma_f32_32x32x16_bf16 v[18:33], v[4:7], v[150:153], v[18:33]
	ds_read_b128 v[4:7], v8 offset:96
	s_waitcnt lgkmcnt(0)
	v_mfma_f32_32x32x16_bf16 v[18:33], v[4:7], v[146:149], v[18:33]
; #define LAS __attribute__((address_space(3)))
; #define MFMA32(a, b, c) __builtin_amdgcn_mfma_f32_32x32x16_bf16((a), (b), (c), 0, 0, 0)
; __device__ __forceinline__ void attn_phase(LAS unsigned char* lds, const bf16* Qg, const bf16* Kg, const bf16* Vg  , bf16* OB, float* LSE, int g, int dsh, int u_lo, int u_hi) {
;     ...
;         for (int c = 0; c < 5; ++c) {
; #pragma unroll
;             for (int i = 0; i < 16; ++i) st[c][i] = 0.f;
;             if (!(first && (wave + c < 4)))
; #pragma unroll
;             for (int ks = 0; ks < 4; ++ks) { const bf16x8 kf = *(const LAS bf16x8*)(Kl + (32 * (wave + c) + r) * AT_PITCH + (16 * ks + 8 * hh) * 2); st[c] = MFMA32(kf, qf[ks], st[c]); } }
.LBB0_143:
	s_or_b64 s[48:49], s[38:39], s[88:89]
	v_cndmask_b32_e64 v3, 0, 1, s[48:49]
	v_cmp_ne_u32_e64 s[44:45], 1, v3
	s_andn2_b64 vcc, exec, s[48:49]
	v_mov_b32_e32 v3, 0
	v_mov_b32_e32 v4, 0
	v_mov_b32_e32 v5, 0
	v_mov_b32_e32 v6, 0
	v_mov_b32_e32 v7, 0
	v_mov_b32_e32 v8, 0
	v_mov_b32_e32 v9, 0
	v_mov_b32_e32 v10, 0
	v_mov_b32_e32 v11, 0
	v_mov_b32_e32 v12, 0
	v_mov_b32_e32 v13, 0
	v_mov_b32_e32 v14, 0
	v_mov_b32_e32 v15, 0
	v_mov_b32_e32 v16, 0
	v_mov_b32_e32 v17, 0
	s_mov_b32 s58, 0x3f317217
	s_mov_b32 s59, 0x7f800000
	s_cbranch_vccnz .LBB0_145
	v_or_b32_e32 v2, s26, v169
	v_mad_u64_u32 v[38:39], s[36:37], v2, s97, v[0:1]
	ds_read_b128 v[2:5], v38
	ds_read_b128 v[34:37], v38 offset:32
	s_waitcnt lgkmcnt(1)
	v_mfma_f32_32x32x16_bf16 v[2:17], v[2:5], v[158:161], 0
	s_waitcnt lgkmcnt(0)
	v_mfma_f32_32x32x16_bf16 v[2:17], v[34:37], v[154:157], v[2:17]
	ds_read_b128 v[34:37], v38 offset:64
	s_waitcnt lgkmcnt(0)
	v_mfma_f32_32x32x16_bf16 v[2:17], v[34:37], v[150:153], v[2:17]
	ds_read_b128 v[34:37], v38 offset:96
	s_waitcnt lgkmcnt(0)
	v_mfma_f32_32x32x16_bf16 v[2:17], v[34:37], v[146:149], v[2:17]
.LBB0_145:
	s_or_b64 s[50:51], s[38:39], s[4:5]
	v_cndmask_b32_e64 v35, 0, 1, s[50:51]
	v_mov_b32_e32 v34, 0
	v_cmp_ne_u32_e64 s[42:43], 1, v35
	s_andn2_b64 vcc, exec, s[50:51]
	v_mov_b32_e32 v50, 0
	v_mov_b32_e32 v51, 0
	v_mov_b32_e32 v52, 0
	v_mov_b32_e32 v53, 0
	v_mov_b32_e32 v54, 0
	v_mov_b32_e32 v55, 0
	v_mov_b32_e32 v56, 0
	v_mov_b32_e32 v57, 0
	v_mov_b32_e32 v58, 0
	v_mov_b32_e32 v59, 0
	v_mov_b32_e32 v60, 0
	v_mov_b32_e32 v61, 0
	v_mov_b32_e32 v62, 0
	v_mov_b32_e32 v63, 0
	v_mov_b32_e32 v64, 0
	v_mov_b32_e32 v65, 0
	s_cbranch_vccnz .LBB0_147
	v_or_b32_e32 v35, s27, v169
	v_mad_u64_u32 v[40:41], s[36:37], v35, s97, v[0:1]
	ds_read_b128 v[36:39], v40
	s_waitcnt lgkmcnt(0)
	v_mfma_f32_32x32x16_bf16 v[50:65], v[36:39], v[158:161], 0
	ds_read_b128 v[36:39], v40 offset:32
	s_waitcnt lgkmcnt(0)
	v_mfma_f32_32x32x16_bf16 v[50:65], v[36:39], v[154:157], v[50:65]
	ds_read_b128 v[36:39], v40 offset:64
	s_waitcnt lgkmcnt(0)
	v_mfma_f32_32x32x16_bf16 v[50:65], v[36:39], v[150:153], v[50:65]
	ds_read_b128 v[36:39], v40 offset:96
	s_waitcnt lgkmcnt(0)
	v_mfma_f32_32x32x16_bf16 v[50:65], v[36:39], v[146:149], v[50:65]
.LBB0_147:
	s_or_b64 s[52:53], s[38:39], s[12:13]
	v_cndmask_b32_e64 v35, 0, 1, s[52:53]
	v_cmp_ne_u32_e64 s[40:41], 1, v35
	s_andn2_b64 vcc, exec, s[52:53]
	v_mov_b32_e32 v35, 0
	v_mov_b32_e32 v36, 0
	v_mov_b32_e32 v37, 0
	v_mov_b32_e32 v38, 0
	v_mov_b32_e32 v39, 0
	v_mov_b32_e32 v40, 0
	v_mov_b32_e32 v41, 0
	v_mov_b32_e32 v42, 0
	v_mov_b32_e32 v43, 0
	v_mov_b32_e32 v44, 0
	v_mov_b32_e32 v45, 0
	v_mov_b32_e32 v46, 0
	v_mov_b32_e32 v47, 0
	v_mov_b32_e32 v48, 0
	v_mov_b32_e32 v49, 0
	s_cbranch_vccnz .LBB0_149
	v_or_b32_e32 v34, s6, v169
	v_mad_u64_u32 v[70:71], s[36:37], v34, s97, v[0:1]
	ds_read_b128 v[34:37], v70
	ds_read_b128 v[66:69], v70 offset:32
	s_waitcnt lgkmcnt(1)
	v_mfma_f32_32x32x16_bf16 v[34:49], v[34:37], v[158:161], 0
	s_waitcnt lgkmcnt(0)
	v_mfma_f32_32x32x16_bf16 v[34:49], v[66:69], v[154:157], v[34:49]
	ds_read_b128 v[66:69], v70 offset:64
	s_waitcnt lgkmcnt(0)
	v_mfma_f32_32x32x16_bf16 v[34:49], v[66:69], v[150:153], v[34:49]
	ds_read_b128 v[66:69], v70 offset:96
	s_waitcnt lgkmcnt(0)
	v_mfma_f32_32x32x16_bf16 v[34:49], v[66:69], v[146:149], v[34:49]
.LBB0_149:
	s_or_b64 s[56:57], s[38:39], s[16:17]
	v_cndmask_b32_e64 v67, 0, 1, s[56:57]
	v_mov_b32_e32 v66, 0
	v_cmp_ne_u32_e64 s[38:39], 1, v67
	s_andn2_b64 vcc, exec, s[56:57]
	v_mov_b32_e32 v67, 0
	v_mov_b32_e32 v68, 0
	v_mov_b32_e32 v69, 0
	v_mov_b32_e32 v70, 0
	v_mov_b32_e32 v71, 0
	v_mov_b32_e32 v72, 0
	v_mov_b32_e32 v73, 0
	v_mov_b32_e32 v74, 0
	v_mov_b32_e32 v75, 0
	v_mov_b32_e32 v76, 0
	v_mov_b32_e32 v77, 0
	v_mov_b32_e32 v78, 0
	v_mov_b32_e32 v79, 0
	v_mov_b32_e32 v80, 0
	v_mov_b32_e32 v81, 0
	s_cbranch_vccnz .LBB0_151
	v_or_b32_e32 v66, s7, v169
	v_mad_u64_u32 v[170:171], s[36:37], v66, s97, v[0:1]
	ds_read_b128 v[66:69], v170
	s_waitcnt lgkmcnt(0)
	v_mfma_f32_32x32x16_bf16 v[66:81], v[66:69], v[158:161], 0
	ds_read_b128 v[158:161], v170 offset:32
	s_waitcnt lgkmcnt(0)
	v_mfma_f32_32x32x16_bf16 v[66:81], v[158:161], v[154:157], v[66:81]
	ds_read_b128 v[154:157], v170 offset:64
	s_waitcnt lgkmcnt(0)
	v_mfma_f32_32x32x16_bf16 v[66:81], v[154:157], v[150:153], v[66:81]
	ds_read_b128 v[150:153], v170 offset:96
	s_waitcnt lgkmcnt(0)
	v_mfma_f32_32x32x16_bf16 v[66:81], v[150:153], v[146:149], v[66:81]
; __device__ __forceinline__ void attn_phase(LAS unsigned char* lds, const bf16* Qg, const bf16* Kg, const bf16* Vg  , bf16* OB, float* LSE, int g, int dsh, int u_lo, int u_hi) {
;     ...
;         for (int c = 0; c < 5; ++c) {
;             const bool dead = first && (wave + c < 4);
; #pragma unroll
;             for (int i = 0; i < 16; ++i) { const int kr = (i & 3) + 8 * (i >> 2) + 4 * hh; bool ok = !dead;
;                 if (c == 0) ok = ok && (kr >= r); if (c == 4) ok = ok && (kr <= r);
;                 if (!ok) st[c][i] = -INFINITY; } }
;         float mx = -INFINITY;
; #pragma unroll
;         for (int c = 0; c < 5; ++c)
; #pragma unroll
;             for (int i = 0; i < 16; ++i) mx = fmaxf(mx, st[c][i]);
.LBB0_151:
	v_lshlrev_b32_e32 v0, 2, v168
	v_cmp_ge_u32_e32 vcc, v0, v169
	s_and_b64 vcc, s[54:55], vcc
	v_or_b32_e32 v146, 1, v0
	v_cndmask_b32_e32 v18, v197, v18, vcc
	v_cmp_ge_u32_e32 vcc, v146, v169
	s_and_b64 vcc, s[54:55], vcc
	v_or_b32_e32 v146, 2, v0
	v_cndmask_b32_e32 v19, v197, v19, vcc
	v_cmp_ge_u32_e32 vcc, v146, v169
	s_and_b64 vcc, s[54:55], vcc
	v_or_b32_e32 v147, 3, v0
	v_cndmask_b32_e32 v20, v197, v20, vcc
	v_cmp_ge_u32_e32 vcc, v147, v169
	s_and_b64 vcc, s[54:55], vcc
	v_or_b32_e32 v148, 8, v0
	v_cndmask_b32_e32 v21, v197, v21, vcc
	v_cmp_ge_u32_e32 vcc, v148, v169
	s_and_b64 vcc, s[54:55], vcc
	v_or_b32_e32 v149, 9, v0
	v_cndmask_b32_e32 v22, v197, v22, vcc
	v_cmp_ge_u32_e32 vcc, v149, v169
	s_and_b64 vcc, s[54:55], vcc
	v_or_b32_e32 v150, 10, v0
	v_cndmask_b32_e32 v23, v197, v23, vcc
	v_cmp_ge_u32_e32 vcc, v150, v169
	s_and_b64 vcc, s[54:55], vcc
	v_or_b32_e32 v151, 11, v0
	v_cndmask_b32_e32 v24, v197, v24, vcc
	v_cmp_ge_u32_e32 vcc, v151, v169
	s_and_b64 vcc, s[54:55], vcc
	v_or_b32_e32 v152, 16, v0
	v_cndmask_b32_e32 v25, v197, v25, vcc
	v_cmp_ge_u32_e32 vcc, v152, v169
	s_and_b64 vcc, s[54:55], vcc
	v_or_b32_e32 v153, 17, v0
	v_cndmask_b32_e32 v26, v197, v26, vcc
	v_cmp_ge_u32_e32 vcc, v153, v169
	s_and_b64 vcc, s[54:55], vcc
	v_or_b32_e32 v154, 18, v0
	v_cndmask_b32_e32 v27, v197, v27, vcc
	v_cmp_ge_u32_e32 vcc, v154, v169
	s_and_b64 vcc, s[54:55], vcc
	v_or_b32_e32 v155, 19, v0
	v_cndmask_b32_e32 v28, v197, v28, vcc
	v_cmp_ge_u32_e32 vcc, v155, v169
	s_and_b64 vcc, s[54:55], vcc
	v_or_b32_e32 v156, 24, v0
	v_cndmask_b32_e32 v29, v197, v29, vcc
	v_cmp_ge_u32_e32 vcc, v156, v169
	s_and_b64 vcc, s[54:55], vcc
	v_or_b32_e32 v157, 25, v0
	v_cndmask_b32_e32 v30, v197, v30, vcc
	v_cmp_ge_u32_e32 vcc, v157, v169
	s_mov_b32 s23, 0xff800000
	s_and_b64 vcc, s[54:55], vcc
	v_or_b32_e32 v158, 26, v0
	v_cndmask_b32_e64 v181, v197, v2, s[48:49]
	v_max3_f32 v2, v18, s23, v19
	v_cndmask_b32_e32 v31, v197, v31, vcc
	v_cmp_ge_u32_e32 vcc, v158, v169
	v_max3_f32 v2, v2, v20, v21
	s_and_b64 vcc, s[54:55], vcc
	v_or_b32_e32 v159, 27, v0
	v_max3_f32 v2, v2, v22, v23
	v_cndmask_b32_e32 v32, v197, v32, vcc
	v_cmp_ge_u32_e32 vcc, v159, v169
	v_max3_f32 v2, v2, v24, v25
	s_and_b64 vcc, s[54:55], vcc
	v_max3_f32 v2, v2, v26, v27
	v_cndmask_b32_e32 v33, v197, v33, vcc
	v_cmp_le_u32_e32 vcc, v0, v169
	v_max3_f32 v2, v2, v28, v29
	s_and_b64 vcc, s[56:57], vcc
	v_max3_f32 v2, v2, v30, v31
	v_cndmask_b32_e64 v182, v197, v3, s[48:49]
	v_cndmask_b32_e32 v66, v197, v66, vcc
	v_cmp_lt_u32_e32 vcc, v0, v169
	v_max3_f32 v2, v2, v32, v33
	v_cndmask_b32_e64 v180, v197, v5, s[48:49]
	v_cndmask_b32_e64 v183, v197, v4, s[48:49]
	s_and_b64 vcc, s[56:57], vcc
	v_max3_f32 v2, v2, v181, v182
	v_cndmask_b32_e64 v178, v197, v7, s[48:49]
	v_cndmask_b32_e64 v179, v197, v6, s[48:49]
	v_cndmask_b32_e32 v67, v197, v67, vcc
	v_cmp_le_u32_e32 vcc, v146, v169
	v_max3_f32 v2, v2, v183, v180
	v_cndmask_b32_e64 v176, v197, v9, s[48:49]
	v_cndmask_b32_e64 v177, v197, v8, s[48:49]
	s_and_b64 vcc, s[56:57], vcc
	v_max3_f32 v2, v2, v179, v178
	v_cndmask_b32_e64 v174, v197, v11, s[48:49]
	v_cndmask_b32_e64 v173, v197, v10, s[48:49]
	v_cndmask_b32_e32 v199, v197, v68, vcc
	v_cmp_le_u32_e32 vcc, v147, v169
	v_max3_f32 v2, v2, v177, v176
	v_cndmask_b32_e64 v172, v197, v13, s[48:49]
	v_cndmask_b32_e64 v175, v197, v12, s[48:49]
	s_and_b64 vcc, s[56:57], vcc
	v_max3_f32 v2, v2, v173, v174
	v_cndmask_b32_e64 v170, v197, v15, s[48:49]
	v_cndmask_b32_e64 v171, v197, v14, s[48:49]
	v_cndmask_b32_e32 v200, v197, v69, vcc
	v_cmp_le_u32_e32 vcc, v148, v169
	v_max3_f32 v2, v2, v175, v172
	v_cndmask_b32_e64 v160, v197, v17, s[48:49]
	v_cndmask_b32_e64 v161, v197, v16, s[48:49]
	s_and_b64 vcc, s[56:57], vcc
	v_max3_f32 v2, v2, v171, v170
	v_cndmask_b32_e64 v51, v197, v51, s[50:51]
	v_cndmask_b32_e64 v50, v197, v50, s[50:51]
	v_cndmask_b32_e32 v148, v197, v70, vcc
	v_cmp_le_u32_e32 vcc, v149, v169
	v_max3_f32 v2, v2, v161, v160
	v_cndmask_b32_e64 v53, v197, v53, s[50:51]
	v_cndmask_b32_e64 v52, v197, v52, s[50:51]
	s_and_b64 vcc, s[56:57], vcc
	v_max3_f32 v2, v2, v50, v51
	v_cndmask_b32_e64 v55, v197, v55, s[50:51]
	v_cndmask_b32_e64 v54, v197, v54, s[50:51]
	v_cndmask_b32_e32 v201, v197, v71, vcc
	v_cmp_le_u32_e32 vcc, v150, v169
	v_max3_f32 v2, v2, v52, v53
	v_cndmask_b32_e64 v57, v197, v57, s[50:51]
	v_cndmask_b32_e64 v56, v197, v56, s[50:51]
	s_and_b64 vcc, s[56:57], vcc
	v_max3_f32 v2, v2, v54, v55
	v_cndmask_b32_e64 v59, v197, v59, s[50:51]
	v_cndmask_b32_e64 v58, v197, v58, s[50:51]
	v_cndmask_b32_e32 v202, v197, v72, vcc
	v_cmp_le_u32_e32 vcc, v151, v169
	v_max3_f32 v2, v2, v56, v57
	v_cndmask_b32_e64 v61, v197, v61, s[50:51]
	v_cndmask_b32_e64 v60, v197, v60, s[50:51]
	s_and_b64 vcc, s[56:57], vcc
	v_max3_f32 v2, v2, v58, v59
	v_cndmask_b32_e64 v63, v197, v63, s[50:51]
	v_cndmask_b32_e64 v62, v197, v62, s[50:51]
	v_cndmask_b32_e32 v203, v197, v73, vcc
	v_cmp_le_u32_e32 vcc, v152, v169
	v_max3_f32 v2, v2, v60, v61
	v_cndmask_b32_e64 v65, v197, v65, s[50:51]
	v_cndmask_b32_e64 v64, v197, v64, s[50:51]
	s_and_b64 vcc, s[56:57], vcc
	v_max3_f32 v2, v2, v62, v63
	v_cndmask_b32_e64 v35, v197, v35, s[52:53]
	v_cndmask_b32_e64 v34, v197, v34, s[52:53]
	v_cndmask_b32_e32 v204, v197, v74, vcc
	v_cmp_le_u32_e32 vcc, v153, v169
	v_max3_f32 v2, v2, v64, v65
	v_cndmask_b32_e64 v37, v197, v37, s[52:53]
	v_cndmask_b32_e64 v36, v197, v36, s[52:53]
	s_and_b64 vcc, s[56:57], vcc
	v_max3_f32 v2, v2, v34, v35
	v_cndmask_b32_e64 v39, v197, v39, s[52:53]
	v_cndmask_b32_e64 v38, v197, v38, s[52:53]
	v_cndmask_b32_e32 v205, v197, v75, vcc
	v_cmp_le_u32_e32 vcc, v154, v169
	v_max3_f32 v2, v2, v36, v37
; __device__ __forceinline__ void attn_phase(LAS unsigned char* lds, const bf16* Qg, const bf16* Kg, const bf16* Vg  , bf16* OB, float* LSE, int g, int dsh, int u_lo, int u_hi) {
;     ...
;         float mx = -INFINITY;
; #pragma unroll
;         for (int c = 0; c < 5; ++c)
; #pragma unroll
;             for (int i = 0; i < 16; ++i) mx = fmaxf(mx, st[c][i]);
;         mx = fmaxf(mx, __shfl_xor(mx, 32));
;         float l = 0.f; const float nmx = -mx * C2;
; #pragma unroll
;         for (int c = 0; c < 5; ++c)
; #pragma unroll
;             for (int i = 0; i < 16; ++i) { const float p = __builtin_amdgcn_exp2f(__builtin_fmaf(st[c][i], C2, nmx)); st[c][i] = p; l += p; }
;         l += __shfl_xor(l, 32);
	v_cndmask_b32_e64 v41, v197, v41, s[52:53]
	v_cndmask_b32_e64 v40, v197, v40, s[52:53]
	s_and_b64 vcc, s[56:57], vcc
	v_max3_f32 v2, v2, v38, v39
	v_cndmask_b32_e64 v43, v197, v43, s[52:53]
	v_cndmask_b32_e64 v42, v197, v42, s[52:53]
	v_cndmask_b32_e32 v206, v197, v76, vcc
	v_cmp_le_u32_e32 vcc, v155, v169
	v_max3_f32 v2, v2, v40, v41
	v_cndmask_b32_e64 v45, v197, v45, s[52:53]
	v_cndmask_b32_e64 v44, v197, v44, s[52:53]
	s_and_b64 vcc, s[56:57], vcc
	v_max3_f32 v2, v2, v42, v43
	v_cndmask_b32_e64 v47, v197, v47, s[52:53]
	v_cndmask_b32_e64 v46, v197, v46, s[52:53]
	v_cndmask_b32_e32 v207, v197, v77, vcc
	v_cmp_le_u32_e32 vcc, v156, v169
	v_max3_f32 v2, v2, v44, v45
	v_cndmask_b32_e64 v189, v197, v49, s[52:53]
	v_cndmask_b32_e64 v48, v197, v48, s[52:53]
	s_and_b64 vcc, s[56:57], vcc
	v_max3_f32 v2, v2, v46, v47
	v_cndmask_b32_e32 v208, v197, v78, vcc
	v_cmp_le_u32_e32 vcc, v157, v169
	v_max3_f32 v2, v2, v48, v189
	s_and_b64 vcc, s[56:57], vcc
	v_max3_f32 v2, v2, v66, v67
	v_cndmask_b32_e32 v209, v197, v79, vcc
	v_cmp_le_u32_e32 vcc, v158, v169
	v_max3_f32 v2, v2, v199, v200
	s_and_b64 vcc, s[56:57], vcc
	v_max3_f32 v2, v2, v148, v201
	v_cndmask_b32_e32 v210, v197, v80, vcc
	v_cmp_le_u32_e32 vcc, v159, v169
	v_max3_f32 v2, v2, v202, v203
	s_and_b64 vcc, s[56:57], vcc
	v_max3_f32 v2, v2, v204, v205
	v_xor_b32_e32 v3, 32, v190
	v_add_u32_e32 v4, 64, v191
	v_cndmask_b32_e32 v211, v197, v81, vcc
	v_max3_f32 v2, v2, v206, v207
	v_cmp_lt_i32_e32 vcc, v3, v4
	v_max3_f32 v2, v2, v208, v209
	v_max3_f32 v2, v2, v210, v211
	v_cndmask_b32_e32 v3, v190, v3, vcc
	v_lshlrev_b32_e32 v212, 2, v3
	ds_bpermute_b32 v3, v212, v2
	v_lshlrev_b32_e32 v213, 3, v167
	s_and_b64 vcc, exec, s[46:47]
	s_waitcnt lgkmcnt(0)
	v_max_f32_e32 v3, v3, v3
	v_max_f32_e32 v49, v2, v3
	v_mul_f32_e32 v214, 0xbe38aa3b, v49
	v_fmamk_f32 v2, v18, 0x3e38aa3b, v214
	v_exp_f32_e32 v10, v2
	v_fmamk_f32 v2, v19, 0x3e38aa3b, v214
	v_exp_f32_e32 v11, v2
	v_fmamk_f32 v2, v20, 0x3e38aa3b, v214
	v_exp_f32_e32 v12, v2
	v_fmamk_f32 v2, v21, 0x3e38aa3b, v214
	v_exp_f32_e32 v13, v2
	v_fmamk_f32 v3, v22, 0x3e38aa3b, v214
	v_add_f32_e32 v2, 0, v10
	v_exp_f32_e32 v14, v3
	v_fmamk_f32 v3, v23, 0x3e38aa3b, v214
	v_add_f32_e32 v2, v11, v2
	v_exp_f32_e32 v15, v3
	v_fmamk_f32 v3, v24, 0x3e38aa3b, v214
	v_add_f32_e32 v2, v12, v2
	v_exp_f32_e32 v16, v3
	v_fmamk_f32 v3, v25, 0x3e38aa3b, v214
	v_add_f32_e32 v2, v13, v2
	v_exp_f32_e32 v17, v3
	v_add_f32_e32 v2, v14, v2
	v_add_f32_e32 v2, v15, v2
	v_add_f32_e32 v2, v16, v2
	v_add_f32_e32 v6, v17, v2
	v_fmamk_f32 v2, v26, 0x3e38aa3b, v214
	v_exp_f32_e32 v2, v2
	v_fmamk_f32 v3, v27, 0x3e38aa3b, v214
	v_exp_f32_e32 v3, v3
	v_fmamk_f32 v4, v28, 0x3e38aa3b, v214
	v_exp_f32_e32 v4, v4
	v_fmamk_f32 v5, v29, 0x3e38aa3b, v214
	v_exp_f32_e32 v5, v5
	v_add_f32_e32 v6, v2, v6
	v_add_f32_e32 v6, v3, v6
	v_add_f32_e32 v6, v4, v6
	v_add_f32_e32 v18, v5, v6
	v_fmamk_f32 v6, v30, 0x3e38aa3b, v214
	v_exp_f32_e32 v6, v6
	v_fmamk_f32 v7, v31, 0x3e38aa3b, v214
	v_exp_f32_e32 v7, v7
	v_fmamk_f32 v8, v32, 0x3e38aa3b, v214
	v_exp_f32_e32 v8, v8
	v_fmamk_f32 v9, v33, 0x3e38aa3b, v214
	v_exp_f32_e32 v9, v9
	v_fmamk_f32 v19, v181, 0x3e38aa3b, v214
	v_add_f32_e32 v18, v6, v18
	v_exp_f32_e32 v181, v19
	v_fmamk_f32 v19, v182, 0x3e38aa3b, v214
	v_add_f32_e32 v18, v7, v18
	v_exp_f32_e32 v182, v19
	v_fmamk_f32 v19, v183, 0x3e38aa3b, v214
	v_add_f32_e32 v18, v8, v18
	v_exp_f32_e32 v183, v19
	v_fmamk_f32 v19, v180, 0x3e38aa3b, v214
	v_add_f32_e32 v18, v9, v18
	v_exp_f32_e32 v184, v19
	v_fmamk_f32 v19, v179, 0x3e38aa3b, v214
	v_add_f32_e32 v18, v181, v18
	v_exp_f32_e32 v185, v19
	v_fmamk_f32 v19, v178, 0x3e38aa3b, v214
	v_add_f32_e32 v18, v182, v18
	v_exp_f32_e32 v186, v19
	v_fmamk_f32 v19, v177, 0x3e38aa3b, v214
	v_add_f32_e32 v18, v183, v18
	v_exp_f32_e32 v187, v19
	v_fmamk_f32 v19, v176, 0x3e38aa3b, v214
	v_add_f32_e32 v18, v184, v18
	v_exp_f32_e32 v188, v19
	v_fmamk_f32 v19, v173, 0x3e38aa3b, v214
	v_add_f32_e32 v18, v185, v18
	v_exp_f32_e32 v173, v19
	v_fmamk_f32 v19, v174, 0x3e38aa3b, v214
	v_add_f32_e32 v18, v186, v18
	v_exp_f32_e32 v174, v19
	v_fmamk_f32 v19, v175, 0x3e38aa3b, v214
	v_add_f32_e32 v18, v187, v18
	v_exp_f32_e32 v175, v19
	v_fmamk_f32 v19, v172, 0x3e38aa3b, v214
	v_add_f32_e32 v18, v188, v18
	v_exp_f32_e32 v176, v19
	v_fmamk_f32 v19, v171, 0x3e38aa3b, v214
	v_add_f32_e32 v18, v173, v18
	v_exp_f32_e32 v177, v19
	v_fmamk_f32 v19, v170, 0x3e38aa3b, v214
	v_add_f32_e32 v18, v174, v18
	v_exp_f32_e32 v178, v19
	v_fmamk_f32 v19, v161, 0x3e38aa3b, v214
	v_add_f32_e32 v18, v175, v18
	v_exp_f32_e32 v179, v19
	v_fmamk_f32 v19, v160, 0x3e38aa3b, v214
	v_add_f32_e32 v18, v176, v18
	v_exp_f32_e32 v180, v19
	v_fmamk_f32 v19, v50, 0x3e38aa3b, v214
	v_add_f32_e32 v18, v177, v18
	v_exp_f32_e32 v157, v19
	v_fmamk_f32 v19, v51, 0x3e38aa3b, v214
	v_add_f32_e32 v18, v178, v18
	v_exp_f32_e32 v158, v19
	v_fmamk_f32 v19, v52, 0x3e38aa3b, v214
	v_add_f32_e32 v18, v179, v18
	v_exp_f32_e32 v159, v19
	v_fmamk_f32 v19, v53, 0x3e38aa3b, v214
	v_add_f32_e32 v18, v180, v18
	v_exp_f32_e32 v160, v19
	v_fmamk_f32 v19, v54, 0x3e38aa3b, v214
	v_add_f32_e32 v18, v157, v18
	v_exp_f32_e32 v161, v19
	v_fmamk_f32 v19, v55, 0x3e38aa3b, v214
	v_add_f32_e32 v18, v158, v18
	v_exp_f32_e32 v170, v19
	v_fmamk_f32 v19, v56, 0x3e38aa3b, v214
	v_add_f32_e32 v18, v159, v18
	v_exp_f32_e32 v171, v19
; #define LAS __attribute__((address_space(3)))
; #define MFMA32(a, b, c) __builtin_amdgcn_mfma_f32_32x32x16_bf16((a), (b), (c), 0, 0, 0)
; __device__ __forceinline__ unsigned cvtpk(float lo, float hi) { unsigned r; asm volatile("v_cvt_pk_bf16_f32 %0, %1, %2" : "=v"(r) : "v"(lo), "v"(hi)); return r; }
; __device__ __forceinline__ s16x4 tr_read16(LAS const unsigned char* p) { typedef short v4i16_t __attribute__((ext_vector_type(4))); return __builtin_bit_cast(s16x4, __builtin_amdgcn_ds_read_tr16_b64_v4i16((LAS v4i16_t*)p)); }
; __device__ __forceinline__ void attn_phase(LAS unsigned char* lds, const bf16* Qg, const bf16* Kg, const bf16* Vg  , bf16* OB, float* LSE, int g, int dsh, int u_lo, int u_hi) {
;     ...
;         float l = 0.f; const float nmx = -mx * C2;
; #pragma unroll
;         for (int c = 0; c < 5; ++c)
; #pragma unroll
;             for (int i = 0; i < 16; ++i) { const float p = __builtin_amdgcn_exp2f(__builtin_fmaf(st[c][i], C2, nmx)); st[c][i] = p; l += p; }
;         l += __shfl_xor(l, 32);
;         f32x16 o[2];
; #pragma unroll
;         for (int i = 0; i < 16; ++i) { o[0][i] = 0.f; o[1][i] = 0.f; }
;         const int q4 = (lane & 15) >> 2, p4 = lane & 3, dblk = (lane >> 4) & 1;
; #pragma unroll
;         for (int c = 0; c < 5; ++c)
;             if (!(first && (wave + c < 4)))
; #pragma unroll
;             for (int s = 0; s < 2; ++s) {
;                 v4u pw; pw.x = cvtpk(st[c][8 * s + 0], st[c][8 * s + 1]); pw.y = cvtpk(st[c][8 * s + 2], st[c][8 * s + 3]); pw.z = cvtpk(st[c][8 * s + 4], st[c][8 * s + 5]); pw.w = cvtpk(st[c][8 * s + 6], st[c][8 * s + 7]);
;                 const bf16x8 pf = __builtin_bit_cast(bf16x8, pw);
; #pragma unroll
;                 for (int dt = 0; dt < 2; ++dt) {
;                     LAS const unsigned char* va = Vl + (32 * (wave + c) + 16 * s + 4 * hh + q4) * AT_PITCH + (32 * dt + 16 * dblk) * 2 + 8 * p4;
;                     const s16x4 lo = tr_read16(va), hi = tr_read16(va + 8 * AT_PITCH);
;                     const bf16x8 vf = __builtin_shufflevector(lo, hi, 0, 1, 2, 3, 4, 5, 6, 7);
;                     o[dt] = MFMA32(vf, pf, o[dt]); } }
	v_fmamk_f32 v19, v57, 0x3e38aa3b, v214
	v_add_f32_e32 v18, v160, v18
	v_exp_f32_e32 v172, v19
	v_fmamk_f32 v19, v58, 0x3e38aa3b, v214
	v_add_f32_e32 v18, v161, v18
	v_exp_f32_e32 v149, v19
	v_fmamk_f32 v19, v59, 0x3e38aa3b, v214
	v_add_f32_e32 v18, v170, v18
	v_exp_f32_e32 v150, v19
	v_fmamk_f32 v19, v60, 0x3e38aa3b, v214
	v_add_f32_e32 v18, v171, v18
	v_exp_f32_e32 v151, v19
	v_fmamk_f32 v19, v61, 0x3e38aa3b, v214
	v_add_f32_e32 v18, v172, v18
	v_exp_f32_e32 v152, v19
	v_fmamk_f32 v19, v62, 0x3e38aa3b, v214
	v_add_f32_e32 v18, v149, v18
	v_exp_f32_e32 v153, v19
	v_fmamk_f32 v19, v63, 0x3e38aa3b, v214
	v_add_f32_e32 v18, v150, v18
	v_exp_f32_e32 v154, v19
	v_fmamk_f32 v19, v64, 0x3e38aa3b, v214
	v_add_f32_e32 v18, v151, v18
	v_exp_f32_e32 v155, v19
	v_fmamk_f32 v19, v65, 0x3e38aa3b, v214
	v_add_f32_e32 v18, v152, v18
	v_exp_f32_e32 v156, v19
	v_fmamk_f32 v19, v34, 0x3e38aa3b, v214
	v_add_f32_e32 v18, v153, v18
	v_exp_f32_e32 v76, v19
	v_fmamk_f32 v19, v35, 0x3e38aa3b, v214
	v_add_f32_e32 v18, v154, v18
	v_exp_f32_e32 v77, v19
	v_fmamk_f32 v19, v36, 0x3e38aa3b, v214
	v_add_f32_e32 v18, v155, v18
	v_exp_f32_e32 v78, v19
	v_fmamk_f32 v19, v37, 0x3e38aa3b, v214
	v_add_f32_e32 v18, v156, v18
	v_exp_f32_e32 v79, v19
	v_fmamk_f32 v19, v38, 0x3e38aa3b, v214
	v_add_f32_e32 v18, v76, v18
	v_exp_f32_e32 v80, v19
	v_fmamk_f32 v19, v39, 0x3e38aa3b, v214
	v_add_f32_e32 v18, v77, v18
	v_exp_f32_e32 v81, v19
	v_fmamk_f32 v19, v40, 0x3e38aa3b, v214
	v_add_f32_e32 v18, v78, v18
	v_exp_f32_e32 v146, v19
	v_fmamk_f32 v19, v41, 0x3e38aa3b, v214
	v_add_f32_e32 v18, v79, v18
	v_exp_f32_e32 v147, v19
	v_fmamk_f32 v19, v42, 0x3e38aa3b, v214
	v_add_f32_e32 v18, v80, v18
	v_exp_f32_e32 v68, v19
	v_fmamk_f32 v19, v43, 0x3e38aa3b, v214
	v_add_f32_e32 v18, v81, v18
	v_exp_f32_e32 v69, v19
	v_fmamk_f32 v19, v44, 0x3e38aa3b, v214
	v_add_f32_e32 v18, v146, v18
	v_exp_f32_e32 v70, v19
	v_fmamk_f32 v19, v45, 0x3e38aa3b, v214
	v_add_f32_e32 v18, v147, v18
	v_exp_f32_e32 v71, v19
	v_fmamk_f32 v19, v46, 0x3e38aa3b, v214
	v_add_f32_e32 v18, v68, v18
	v_exp_f32_e32 v72, v19
	v_fmamk_f32 v19, v47, 0x3e38aa3b, v214
	v_add_f32_e32 v18, v69, v18
	v_exp_f32_e32 v73, v19
	v_fmamk_f32 v19, v48, 0x3e38aa3b, v214
	v_add_f32_e32 v18, v70, v18
	v_exp_f32_e32 v74, v19
	v_fmamk_f32 v19, v189, 0x3e38aa3b, v214
	v_add_f32_e32 v18, v71, v18
	v_exp_f32_e32 v75, v19
	v_fmamk_f32 v19, v66, 0x3e38aa3b, v214
	v_add_f32_e32 v18, v72, v18
	v_exp_f32_e32 v60, v19
	v_fmamk_f32 v19, v67, 0x3e38aa3b, v214
	v_add_f32_e32 v18, v73, v18
	v_exp_f32_e32 v61, v19
	v_fmamk_f32 v19, v199, 0x3e38aa3b, v214
	v_add_f32_e32 v18, v74, v18
	v_exp_f32_e32 v62, v19
	v_fmamk_f32 v19, v200, 0x3e38aa3b, v214
	v_add_f32_e32 v18, v75, v18
	v_exp_f32_e32 v63, v19
	v_fmamk_f32 v19, v148, 0x3e38aa3b, v214
	v_add_f32_e32 v18, v60, v18
	v_exp_f32_e32 v64, v19
	v_fmamk_f32 v19, v201, 0x3e38aa3b, v214
	v_add_f32_e32 v18, v61, v18
	v_exp_f32_e32 v65, v19
	v_fmamk_f32 v19, v202, 0x3e38aa3b, v214
	v_add_f32_e32 v18, v62, v18
	v_exp_f32_e32 v66, v19
	v_fmamk_f32 v19, v203, 0x3e38aa3b, v214
	v_add_f32_e32 v18, v63, v18
	v_exp_f32_e32 v67, v19
	v_fmamk_f32 v19, v204, 0x3e38aa3b, v214
	v_add_f32_e32 v18, v64, v18
	v_exp_f32_e32 v52, v19
	v_fmamk_f32 v19, v205, 0x3e38aa3b, v214
	v_add_f32_e32 v18, v65, v18
	v_exp_f32_e32 v53, v19
	v_fmamk_f32 v19, v206, 0x3e38aa3b, v214
	v_add_f32_e32 v18, v66, v18
	v_exp_f32_e32 v54, v19
	v_fmamk_f32 v19, v207, 0x3e38aa3b, v214
	v_add_f32_e32 v18, v67, v18
	v_exp_f32_e32 v55, v19
	v_fmamk_f32 v19, v208, 0x3e38aa3b, v214
	v_add_f32_e32 v18, v52, v18
	v_exp_f32_e32 v56, v19
	v_fmamk_f32 v19, v209, 0x3e38aa3b, v214
	v_add_f32_e32 v18, v53, v18
	v_exp_f32_e32 v57, v19
	v_fmamk_f32 v19, v210, 0x3e38aa3b, v214
	v_add_f32_e32 v18, v54, v18
	v_exp_f32_e32 v58, v19
	v_fmac_f32_e32 v214, 0x3e38aa3b, v211
	v_add_f32_e32 v18, v55, v18
	v_exp_f32_e32 v59, v214
	v_add_f32_e32 v18, v56, v18
	v_add_f32_e32 v18, v57, v18
	v_add_f32_e32 v18, v58, v18
	v_add_f32_e32 v50, v59, v18
	ds_bpermute_b32 v51, v212, v50
	v_lshrrev_b32_e32 v18, 2, v167
	v_and_or_b32 v148, v18, 3, v0
	v_lshlrev_b32_e32 v0, 1, v167
	v_and_b32_e32 v0, 32, v0
	v_and_b32_e32 v18, 24, v213
	v_add3_u32 v48, 0, v0, v18
	s_cbranch_vccnz .LBB0_153
	v_or_b32_e32 v0, s14, v148
	v_mad_u64_u32 v[200:201], s[36:37], v0, s97, v[48:49]
	v_cvt_pk_bf16_f32 v10, v10, v11
	v_cvt_pk_bf16_f32 v11, v12, v13
	v_cvt_pk_bf16_f32 v12, v14, v15
	v_cvt_pk_bf16_f32 v13, v16, v17
	ds_read_b64_tr_b16 v[14:15], v200 offset:55296
	ds_read_b64_tr_b16 v[16:17], v200 offset:56448
	s_waitcnt lgkmcnt(0)
	v_mfma_f32_32x32x16_bf16 v[32:47], v[14:17], v[10:13], 0
	ds_read_b64_tr_b16 v[14:15], v200 offset:55360
	ds_read_b64_tr_b16 v[16:17], v200 offset:56512
	v_cvt_pk_bf16_f32 v2, v2, v3
	v_cvt_pk_bf16_f32 v3, v4, v5
	v_cvt_pk_bf16_f32 v4, v6, v7
	v_cvt_pk_bf16_f32 v5, v8, v9
	ds_read_b64_tr_b16 v[6:7], v200 offset:57600
	ds_read_b64_tr_b16 v[8:9], v200 offset:58752
	s_waitcnt lgkmcnt(2)
	v_mfma_f32_32x32x16_bf16 v[16:31], v[14:17], v[10:13], 0
	s_waitcnt lgkmcnt(0)
	v_mfma_f32_32x32x16_bf16 v[32:47], v[6:9], v[2:5], v[32:47]
	ds_read_b64_tr_b16 v[6:7], v200 offset:57664
	ds_read_b64_tr_b16 v[8:9], v200 offset:58816
	s_waitcnt lgkmcnt(0)
	v_mfma_f32_32x32x16_bf16 v[16:31], v[6:9], v[2:5], v[16:31]
	s_mov_b32 s23, 0x800000
	s_and_b64 vcc, exec, s[44:45]
	s_cbranch_vccz .LBB0_154
	s_branch .LBB0_155

; #define GAS __attribute__((address_space(1)))
; __device__ __forceinline__ void attn_phase(LAS unsigned char* lds, const bf16* Qg, const bf16* Kg, const bf16* Vg  , bf16* OB, float* LSE, int g, int dsh, int u_lo, int u_hi) {
;     ...
;         const float inv = 1.0f / l; float lse = mx * 0.125f + __logf(l);
;         float ea = 0.f, eb = 1.f;
;         if (g > 0) { const float lp = ((const GAS float*)LSE)[qtok * 16 + h]; const float mm = fmaxf(lp, lse); ea = __expf(lp - mm); eb = __expf(lse - mm); const float den = 1.0f / (ea + eb); lse = mm + __logf(ea + eb); ea *= den; eb *= den; }
;         eb *= inv;
.LBB0_159:
	s_waitcnt lgkmcnt(0)
	v_add_f32_e32 v0, v50, v51
	v_cmp_gt_f32_e32 vcc, s23, v0
	v_mov_b32_e32 v52, 0
	s_nop 0
	v_cndmask_b32_e64 v2, 0, 32, vcc
	v_ldexp_f32 v2, v0, v2
	v_log_f32_e32 v2, v2
	v_cndmask_b32_e32 v3, 0, v198, vcc
	v_mul_f32_e32 v4, 0x3f317217, v2
	v_fma_f32 v4, v2, s58, -v4
	v_fmac_f32_e32 v4, 0x3377d1cf, v2
	v_fmac_f32_e32 v4, 0x3f317217, v2
	v_cmp_lt_f32_e64 vcc, |v2|, s59
	s_nop 1
	v_cndmask_b32_e32 v2, v2, v4, vcc
	v_sub_f32_e32 v50, v2, v3
	v_lshlrev_b64 v[2:3], 6, v[164:165]
	v_fmac_f32_e32 v50, 0x3e000000, v49
	s_andn2_b64 vcc, exec, s[28:29]
	v_lshl_add_u64 v[48:49], s[86:87], 0, v[2:3]
	s_cbranch_vccnz .LBB0_163
	s_waitcnt vmcnt(16)
	v_mov_b32_e32 v2, v254
	v_max_f32_e32 v4, v50, v50
	v_max_f32_e32 v3, v2, v2
	v_max_f32_e32 v3, v3, v4
	v_sub_f32_e32 v2, v2, v3
	v_sub_f32_e32 v4, v50, v3
	v_mul_f32_e32 v2, 0x3fb8aa3b, v2
	v_mul_f32_e32 v4, 0x3fb8aa3b, v4
	v_exp_f32_e32 v2, v2
	v_exp_f32_e32 v4, v4
	s_nop 0
	v_add_f32_e32 v5, v2, v4
	v_div_scale_f32 v6, s[36:37], v5, v5, 1.0
	v_rcp_f32_e32 v7, v6
	s_nop 0
	v_fma_f32 v8, -v6, v7, 1.0
	v_fmac_f32_e32 v7, v8, v7
	v_div_scale_f32 v8, vcc, 1.0, v5, 1.0
	v_mul_f32_e32 v9, v8, v7
	v_fma_f32 v10, -v6, v9, v8
	v_fmac_f32_e32 v9, v10, v7
	v_fma_f32 v6, -v6, v9, v8
	v_div_fmas_f32 v6, v6, v7, v9
	v_cmp_gt_f32_e32 vcc, s23, v5
	v_div_fixup_f32 v6, v6, v5, 1.0
	v_mul_f32_e32 v52, v2, v6
	v_cndmask_b32_e64 v7, 0, 32, vcc
	v_ldexp_f32 v5, v5, v7
	v_log_f32_e32 v5, v5
	v_mul_f32_e32 v2, v4, v6
	v_mul_f32_e32 v7, 0x3f317217, v5
	v_fma_f32 v7, v5, s58, -v7
	v_fmac_f32_e32 v7, 0x3377d1cf, v5
	v_fmac_f32_e32 v7, 0x3f317217, v5
	v_cmp_lt_f32_e64 s[38:39], |v5|, s59
	s_nop 1
	v_cndmask_b32_e64 v5, v5, v7, s[38:39]
	v_cndmask_b32_e32 v7, 0, v198, vcc
	v_sub_f32_e32 v5, v5, v7
	v_add_f32_e32 v50, v3, v5
	s_branch .LBB0_164

; #define GAS __attribute__((address_space(1)))
; #define LAS __attribute__((address_space(3)))
; __device__ __forceinline__ unsigned cvtpk(float lo, float hi) { unsigned r; asm volatile("v_cvt_pk_bf16_f32 %0, %1, %2" : "=v"(r) : "v"(lo), "v"(hi)); return r; }
; __device__ __forceinline__ void attn_phase(LAS unsigned char* lds, const bf16* Qg, const bf16* Kg, const bf16* Vg  , bf16* OB, float* LSE, int g, int dsh, int u_lo, int u_hi) {
;     ...
;         const float inv = 1.0f / l; float lse = mx * 0.125f + __logf(l);
;         float ea = 0.f, eb = 1.f;
;         if (g > 0) { const float lp = ((const GAS float*)LSE)[qtok * 16 + h]; const float mm = fmaxf(lp, lse); ea = __expf(lp - mm); eb = __expf(lse - mm); const float den = 1.0f / (ea + eb); lse = mm + __logf(ea + eb); ea *= den; eb *= den; }
;         eb *= inv;
;         LAS unsigned char* Ost = lds + 2 * AT_ROWS * AT_PITCH + wave * (32 * 136);
; #pragma unroll
;         for (int dt = 0; dt < 2; ++dt)
; #pragma unroll
;             for (int i4 = 0; i4 < 4; ++i4) { v2u w; w.x = cvtpk(o[dt][4 * i4] * eb, o[dt][4 * i4 + 1] * eb); w.y = cvtpk(o[dt][4 * i4 + 2] * eb, o[dt][4 * i4 + 3] * eb);
;                 *(LAS v2u*)(Ost + r * 136 + (32 * dt + 8 * i4 + 4 * hh) * 2) = w; }
;         asm volatile("s_waitcnt lgkmcnt(0)" ::: "memory");
;         const int rr0 = lane >> 3, cc = lane & 7;
;         v4u pv4[4];
;         if (g > 0) {
; #pragma unroll
;             for (int j4 = 0; j4 < 4; ++j4) pv4[j4] = *(const GAS v4u*)(OB + (tokbase + (size_t)(Q0 + 32 * wave + rr0 + 8 * j4) * dil) * 1024 + h * 64 + cc * 8); }
; #pragma unroll
;         for (int j4 = 0; j4 < 4; ++j4) { const int rr = rr0 + 8 * j4; v4u sv = *(const LAS v4u*)(Ost + rr * 136 + cc * 16);
;             if (g > 0) { const float ear = __shfl(ea, rr); const v4u pq = pv4[j4];
.LBB0_164:
	v_div_scale_f32 v3, s[36:37], v0, v0, 1.0
	v_rcp_f32_e32 v4, v3
	v_lshlrev_b32_e32 v5, 3, v168
	v_and_b32_e32 v51, 63, v167
	s_lshl_b32 s38, s77, 6
	v_fma_f32 v6, -v3, v4, 1.0
	v_fmac_f32_e32 v4, v6, v4
	v_div_scale_f32 v6, vcc, 1.0, v0, 1.0
	v_mul_f32_e32 v7, v6, v4
	v_fma_f32 v8, -v3, v7, v6
	v_fmac_f32_e32 v7, v8, v4
	v_fma_f32 v3, -v3, v7, v6
	v_div_fmas_f32 v3, v3, v4, v7
	v_div_fixup_f32 v0, v3, v0, 1.0
	v_mul_f32_e32 v0, v0, v2
	v_mul_u32_u24_e32 v2, 0x88, v169
	v_add3_u32 v4, s15, v2, v5
	v_mul_f32_e32 v2, v32, v0
	v_mul_f32_e32 v3, v33, v0
	v_cvt_pk_bf16_f32 v2, v2, v3
	v_mul_f32_e32 v3, v34, v0
	v_mul_f32_e32 v5, v35, v0
	v_cvt_pk_bf16_f32 v3, v3, v5
	ds_write_b64 v4, v[2:3]
	v_mul_f32_e32 v2, v36, v0
	v_mul_f32_e32 v3, v37, v0
	v_cvt_pk_bf16_f32 v2, v2, v3
	v_mul_f32_e32 v3, v38, v0
	v_mul_f32_e32 v5, v39, v0
	v_cvt_pk_bf16_f32 v3, v3, v5
	ds_write_b64 v4, v[2:3] offset:16
	v_mul_f32_e32 v2, v40, v0
	v_mul_f32_e32 v3, v41, v0
	v_cvt_pk_bf16_f32 v2, v2, v3
	v_mul_f32_e32 v3, v42, v0
	v_mul_f32_e32 v5, v43, v0
	v_cvt_pk_bf16_f32 v3, v3, v5
	ds_write_b64 v4, v[2:3] offset:32
	v_mul_f32_e32 v2, v44, v0
	v_mul_f32_e32 v3, v45, v0
	v_cvt_pk_bf16_f32 v2, v2, v3
	v_mul_f32_e32 v3, v46, v0
	v_mul_f32_e32 v5, v47, v0
	v_cvt_pk_bf16_f32 v3, v3, v5
	ds_write_b64 v4, v[2:3] offset:48
	v_mul_f32_e32 v2, v16, v0
	v_mul_f32_e32 v3, v17, v0
	v_cvt_pk_bf16_f32 v2, v2, v3
	v_mul_f32_e32 v3, v18, v0
	v_mul_f32_e32 v5, v19, v0
	v_cvt_pk_bf16_f32 v3, v3, v5
	ds_write_b64 v4, v[2:3] offset:64
	v_mul_f32_e32 v2, v20, v0
	v_mul_f32_e32 v3, v21, v0
	v_cvt_pk_bf16_f32 v2, v2, v3
	v_mul_f32_e32 v3, v22, v0
	v_mul_f32_e32 v5, v23, v0
	v_cvt_pk_bf16_f32 v3, v3, v5
	ds_write_b64 v4, v[2:3] offset:80
	v_mul_f32_e32 v2, v24, v0
	v_mul_f32_e32 v3, v25, v0
	v_cvt_pk_bf16_f32 v2, v2, v3
	v_mul_f32_e32 v3, v26, v0
	v_mul_f32_e32 v5, v27, v0
	v_cvt_pk_bf16_f32 v3, v3, v5
	ds_write_b64 v4, v[2:3] offset:96
	v_mul_f32_e32 v2, v28, v0
	v_mul_f32_e32 v3, v29, v0
	v_cvt_pk_bf16_f32 v2, v2, v3
	v_mul_f32_e32 v3, v30, v0
	v_mul_f32_e32 v0, v31, v0
	v_cvt_pk_bf16_f32 v3, v3, v0
	ds_write_b64 v4, v[2:3] offset:112
	s_waitcnt lgkmcnt(0)
	v_lshrrev_b32_e32 v30, 3, v51
	v_and_b32_e32 v18, 7, v167
	v_or_b32_e32 v28, s78, v30
	s_and_b64 vcc, exec, s[28:29]
	v_lshlrev_b32_e32 v0, 3, v18
	v_ashrrev_i32_e32 v29, 31, v28
	s_cbranch_vccz .LBB0_181
	s_waitcnt vmcnt(16)
	v_mov_b64_e32 v[2:3], v[216:217]
	v_mov_b64_e32 v[4:5], v[218:219]
	v_mov_b64_e32 v[6:7], v[220:221]
	v_mov_b64_e32 v[8:9], v[222:223]
	v_mov_b64_e32 v[10:11], v[224:225]
	v_mov_b64_e32 v[12:13], v[226:227]
	v_mov_b64_e32 v[14:15], v[228:229]
	v_mov_b64_e32 v[16:17], v[230:231]
	s_cbranch_execnz .LBB0_167
.LBB0_166:
	v_mov_b64_e32 v[14:15], v[130:131]
	v_mov_b64_e32 v[10:11], v[134:135]
	v_mov_b64_e32 v[6:7], v[138:139]
	v_mov_b64_e32 v[2:3], v[142:143]
	v_mov_b64_e32 v[16:17], v[132:133]
	v_mov_b64_e32 v[12:13], v[136:137]
	v_mov_b64_e32 v[8:9], v[140:141]
	v_mov_b64_e32 v[4:5], v[144:145]

; #define PG8_GAS __attribute__((address_space(1)))
; __device__ __forceinline__ unsigned cvt_pk_bf16(float lo, float hi) { unsigned r; asm volatile("v_cvt_pk_bf16_f32 %0, %1, %2" : "=v"(r) : "v"(lo), "v"(hi)); return r; }
;     __device__ __forceinline__ void operator()(const f32x4 (&acc)[2][2][4][2], const Unit& u, int wr, int wc, int fr, int fq) const {
;         const int row0 = u.pm * BM + wr * 64 + fr; int colt = u.pn * BM; bf16_t* Ob = O;
;         if (split) { const int t = colt >> 10; colt &= 1023; Ob = t == 0 ? O : (t == 1 ? O1 : O2); }
;         const int col0 = colt + wc * 32 + 8 * fq;
;         f32x4 pv[2][4];
; #pragma unroll
;         for (int ai = 0; ai < 2; ++ai)
; #pragma unroll
;             for (int m = 0; m < 4; ++m) pv[ai][m] = *(const PG8_GAS f32x4*)(ssq + (size_t)(row0 + ai * HALF + m * 16) * 16 + 4 * fq);
;         float rsv[2][4];
; #pragma unroll
;         for (int ai = 0; ai < 2; ++ai)
; #pragma unroll
;             for (int m = 0; m < 4; ++m) { float s = (pv[ai][m][0] + pv[ai][m][1]) + (pv[ai][m][2] + pv[ai][m][3]); s += __shfl_xor(s, 16); s += __shfl_xor(s, 32);
;                 rsv[ai][m] = __builtin_amdgcn_rsqf(s * (1.0f / 1024.0f) + NORM_EPS); }
; #pragma unroll
;         for (int ai = 0; ai < 2; ++ai)
; #pragma unroll
;             for (int m = 0; m < 4; ++m) {
;                 const int row = row0 + ai * HALF + m * 16; const float rs = rsv[ai][m];
;                 bf16_t* rowp = Ob + (size_t)row * ldc + col0;
; #pragma unroll
;                 for (int bj = 0; bj < 2; ++bj) { f32x4 v0 = acc[ai][bj][m][0] * rs, v1 = acc[ai][bj][m][1] * rs;
;                     if (ACT == 1) {
; #pragma unroll
;                         for (int e = 0; e < 4; ++e) { const float a = fmaxf(v0[e], 0.f), b = fmaxf(v1[e], 0.f); v0[e] = a * a; v1[e] = b * b; } }
;                     u32x4 w; w.x = cvt_pk_bf16(v0[0], v0[1]); w.y = cvt_pk_bf16(v0[2], v0[3]); w.z = cvt_pk_bf16(v1[0], v1[1]); w.w = cvt_pk_bf16(v1[2], v1[3]);
;                     *(PG8_GAS u32x4*)(rowp + bj * HALF) = w; } }
.Lmy_rstd_ok:
	s_lshl_b32 s2, s27, 8
	s_and_b32 s6, s2, 0x300
	s_cmp_gt_u32 s27, 3
	s_cselect_b64 s[4:5], -1, 0
	s_cmp_lt_u32 s27, 8
	s_cselect_b32 s7, s69, s82
	s_cselect_b32 s9, s68, s83
	s_and_b64 s[4:5], s[24:25], s[4:5]
	s_and_b64 s[4:5], s[4:5], exec
	s_cselect_b32 s9, s9, s57
	s_cselect_b32 s7, s7, s56
	s_and_b64 s[4:5], s[24:25], exec
	s_cselect_b32 s2, s6, s2
	s_cmp_eq_u64 s[24:25], 0
	s_cbranch_scc1 .Lmy_epi_std
	v_readlane_b32 s6, v249, 1
	s_lshl_b32 s6, s6, 1
	s_and_b32 s4, s26, 15
	s_lshl_b32 s4, s4, 8
	v_add_u32_e32 v130, s4, v199
	v_lshrrev_b32_e32 v131, s6, v130
	s_lshl_b32 s4, 1, s6
	s_add_i32 s4, s4, -1
	v_and_b32_e32 v132, s4, v130
	v_lshlrev_b32_e32 v132, 12, v132
	v_lshrrev_b32_e32 v132, s6, v132
	v_or_b32_e32 v133, s2, v201
	v_lshrrev_b32_e32 v134, 6, v133
	v_and_b32_e32 v133, 63, v133
	s_lshr_b32 s4, s26, 4
	s_lshl_b32 s4, s4, 4
	v_add_u32_e32 v134, s4, v134
	v_lshlrev_b32_e32 v134, 12, v134
	v_add3_u32 v134, v134, v132, v131
	v_lshlrev_b32_e32 v134, 7, v134
	v_lshl_add_u32 v134, v133, 1, v134
	v_mov_b32_e32 v135, 0
	v_mov_b32_e32 v142, s7
	v_mov_b32_e32 v143, s9
	v_lshl_add_u64 v[140:141], v[134:135], 0, v[142:143]
	s_mov_b64 s[4:5], 0x100000
	v_lshl_add_u64 v[142:143], v[140:141], 0, s[4:5]
	s_lshr_b32 s4, 0x2800, s6
	s_mov_b32 s5, 0
	s_lshr_b32 s6, 0x800, s6
	s_mov_b32 s7, 0
	s_branch .Lmy_epi_ptr_done
.Lmy_epi_std:
	v_or_b32_e32 v140, s2, v201
	v_mov_b32_e32 v141, 0
	v_mov_b32_e32 v142, s7
	v_mov_b32_e32 v143, s9
	v_lshl_add_u64 v[140:141], v[140:141], 1, v[142:143]
	v_lshl_add_u32 v130, s26, 8, v199
	s_lshl_b32 s6, s11, 1
	v_mul_lo_u32 v142, v130, s6
	v_mov_b32_e32 v143, 0
	v_lshl_add_u64 v[140:141], v[140:141], 0, v[142:143]
	s_movk_i32 s6, 0x100
	s_mov_b32 s7, 0
	v_lshl_add_u64 v[142:143], v[140:141], 0, s[6:7]
	s_lshl_b32 s6, s11, 5
	s_mul_i32 s4, s11, 0xa0
	s_mov_b32 s5, 0
.Lmy_epi_ptr_done:
	s_cmp_eq_u32 s15, 1
	s_cbranch_scc1 .Lmy_epi_relu2
	v_pk_mul_f32 v[144:145], v[126:127], v[236:237] op_sel_hi:[1,0]
	v_pk_mul_f32 v[146:147], v[128:129], v[236:237] op_sel_hi:[1,0]
	v_pk_mul_f32 v[148:149], v[122:123], v[236:237] op_sel_hi:[1,0]
	v_pk_mul_f32 v[150:151], v[124:125], v[236:237] op_sel_hi:[1,0]
	v_cvt_pk_bf16_f32 v152, v144, v145
	v_cvt_pk_bf16_f32 v153, v146, v147
	v_cvt_pk_bf16_f32 v154, v148, v149
	v_cvt_pk_bf16_f32 v155, v150, v151
	global_store_dwordx4 v[140:141], v[152:155], off
	v_pk_mul_f32 v[172:173], v[118:119], v[236:237] op_sel_hi:[1,0]
	v_pk_mul_f32 v[174:175], v[120:121], v[236:237] op_sel_hi:[1,0]
	v_pk_mul_f32 v[176:177], v[114:115], v[236:237] op_sel_hi:[1,0]
	v_pk_mul_f32 v[178:179], v[116:117], v[236:237] op_sel_hi:[1,0]
	v_cvt_pk_bf16_f32 v180, v172, v173
	v_cvt_pk_bf16_f32 v181, v174, v175
	v_cvt_pk_bf16_f32 v182, v176, v177
	v_cvt_pk_bf16_f32 v183, v178, v179
	global_store_dwordx4 v[142:143], v[180:183], off
	v_lshl_add_u64 v[140:141], v[140:141], 0, s[6:7]
	v_lshl_add_u64 v[142:143], v[142:143], 0, s[6:7]
	v_pk_mul_f32 v[144:145], v[110:111], v[238:239] op_sel_hi:[1,0]
	v_pk_mul_f32 v[146:147], v[112:113], v[238:239] op_sel_hi:[1,0]
	v_pk_mul_f32 v[148:149], v[106:107], v[238:239] op_sel_hi:[1,0]
	v_pk_mul_f32 v[150:151], v[108:109], v[238:239] op_sel_hi:[1,0]
	v_cvt_pk_bf16_f32 v152, v144, v145
	v_cvt_pk_bf16_f32 v153, v146, v147
	v_cvt_pk_bf16_f32 v154, v148, v149
	v_cvt_pk_bf16_f32 v155, v150, v151
	global_store_dwordx4 v[140:141], v[152:155], off
	v_pk_mul_f32 v[172:173], v[102:103], v[238:239] op_sel_hi:[1,0]
	v_pk_mul_f32 v[174:175], v[104:105], v[238:239] op_sel_hi:[1,0]
	v_pk_mul_f32 v[176:177], v[98:99], v[238:239] op_sel_hi:[1,0]
	v_pk_mul_f32 v[178:179], v[100:101], v[238:239] op_sel_hi:[1,0]
	v_cvt_pk_bf16_f32 v180, v172, v173
	v_cvt_pk_bf16_f32 v181, v174, v175
	v_cvt_pk_bf16_f32 v182, v176, v177
	v_cvt_pk_bf16_f32 v183, v178, v179
	global_store_dwordx4 v[142:143], v[180:183], off
	v_lshl_add_u64 v[140:141], v[140:141], 0, s[6:7]
	v_lshl_add_u64 v[142:143], v[142:143], 0, s[6:7]
	v_pk_mul_f32 v[144:145], v[94:95], v[240:241] op_sel_hi:[1,0]
	v_pk_mul_f32 v[146:147], v[96:97], v[240:241] op_sel_hi:[1,0]
	v_pk_mul_f32 v[148:149], v[90:91], v[240:241] op_sel_hi:[1,0]
	v_pk_mul_f32 v[150:151], v[92:93], v[240:241] op_sel_hi:[1,0]
	v_cvt_pk_bf16_f32 v152, v144, v145
	v_cvt_pk_bf16_f32 v153, v146, v147
	v_cvt_pk_bf16_f32 v154, v148, v149
	v_cvt_pk_bf16_f32 v155, v150, v151
	global_store_dwordx4 v[140:141], v[152:155], off
	v_pk_mul_f32 v[172:173], v[86:87], v[240:241] op_sel_hi:[1,0]
	v_pk_mul_f32 v[174:175], v[88:89], v[240:241] op_sel_hi:[1,0]
	v_pk_mul_f32 v[176:177], v[82:83], v[240:241] op_sel_hi:[1,0]
	v_pk_mul_f32 v[178:179], v[84:85], v[240:241] op_sel_hi:[1,0]
	v_cvt_pk_bf16_f32 v180, v172, v173
	v_cvt_pk_bf16_f32 v181, v174, v175
	v_cvt_pk_bf16_f32 v182, v176, v177
	v_cvt_pk_bf16_f32 v183, v178, v179
	global_store_dwordx4 v[142:143], v[180:183], off
	v_lshl_add_u64 v[140:141], v[140:141], 0, s[6:7]
	v_lshl_add_u64 v[142:143], v[142:143], 0, s[6:7]
	v_pk_mul_f32 v[144:145], v[78:79], v[242:243] op_sel_hi:[1,0]
	v_pk_mul_f32 v[146:147], v[80:81], v[242:243] op_sel_hi:[1,0]
	v_pk_mul_f32 v[148:149], v[74:75], v[242:243] op_sel_hi:[1,0]
	v_pk_mul_f32 v[150:151], v[76:77], v[242:243] op_sel_hi:[1,0]
	v_cvt_pk_bf16_f32 v152, v144, v145
	v_cvt_pk_bf16_f32 v153, v146, v147
	v_cvt_pk_bf16_f32 v154, v148, v149
	v_cvt_pk_bf16_f32 v155, v150, v151
	global_store_dwordx4 v[140:141], v[152:155], off
	v_pk_mul_f32 v[172:173], v[70:71], v[242:243] op_sel_hi:[1,0]
	v_pk_mul_f32 v[174:175], v[72:73], v[242:243] op_sel_hi:[1,0]
	v_pk_mul_f32 v[176:177], v[66:67], v[242:243] op_sel_hi:[1,0]
	v_pk_mul_f32 v[178:179], v[68:69], v[242:243] op_sel_hi:[1,0]
	v_cvt_pk_bf16_f32 v180, v172, v173
; #define PG8_GAS __attribute__((address_space(1)))
; __device__ __forceinline__ unsigned cvt_pk_bf16(float lo, float hi) { unsigned r; asm volatile("v_cvt_pk_bf16_f32 %0, %1, %2" : "=v"(r) : "v"(lo), "v"(hi)); return r; }
;     __device__ __forceinline__ void operator()(const f32x4 (&acc)[2][2][4][2], const Unit& u, int wr, int wc, int fr, int fq) const {
;     ...
;             for (int m = 0; m < 4; ++m) {
;                 const int row = row0 + ai * HALF + m * 16; const float rs = rsv[ai][m];
;                 bf16_t* rowp = Ob + (size_t)row * ldc + col0;
; #pragma unroll
;                 for (int bj = 0; bj < 2; ++bj) { f32x4 v0 = acc[ai][bj][m][0] * rs, v1 = acc[ai][bj][m][1] * rs;
;                     if (ACT == 1) {
; #pragma unroll
;                         for (int e = 0; e < 4; ++e) { const float a = fmaxf(v0[e], 0.f), b = fmaxf(v1[e], 0.f); v0[e] = a * a; v1[e] = b * b; } }
;                     u32x4 w; w.x = cvt_pk_bf16(v0[0], v0[1]); w.y = cvt_pk_bf16(v0[2], v0[3]); w.z = cvt_pk_bf16(v1[0], v1[1]); w.w = cvt_pk_bf16(v1[2], v1[3]);
;                     *(PG8_GAS u32x4*)(rowp + bj * HALF) = w; } }
	v_cvt_pk_bf16_f32 v181, v174, v175
	v_cvt_pk_bf16_f32 v182, v176, v177
	v_cvt_pk_bf16_f32 v183, v178, v179
	global_store_dwordx4 v[142:143], v[180:183], off
	v_lshl_add_u64 v[140:141], v[140:141], 0, s[4:5]
	v_lshl_add_u64 v[142:143], v[142:143], 0, s[4:5]
	v_pk_mul_f32 v[144:145], v[62:63], v[244:245] op_sel_hi:[1,0]
	v_pk_mul_f32 v[146:147], v[64:65], v[244:245] op_sel_hi:[1,0]
	v_pk_mul_f32 v[148:149], v[58:59], v[244:245] op_sel_hi:[1,0]
	v_pk_mul_f32 v[150:151], v[60:61], v[244:245] op_sel_hi:[1,0]
	v_cvt_pk_bf16_f32 v152, v144, v145
	v_cvt_pk_bf16_f32 v153, v146, v147
	v_cvt_pk_bf16_f32 v154, v148, v149
	v_cvt_pk_bf16_f32 v155, v150, v151
	global_store_dwordx4 v[140:141], v[152:155], off
	v_pk_mul_f32 v[172:173], v[54:55], v[244:245] op_sel_hi:[1,0]
	v_pk_mul_f32 v[174:175], v[56:57], v[244:245] op_sel_hi:[1,0]
	v_pk_mul_f32 v[176:177], v[50:51], v[244:245] op_sel_hi:[1,0]
	v_pk_mul_f32 v[178:179], v[52:53], v[244:245] op_sel_hi:[1,0]
	v_cvt_pk_bf16_f32 v180, v172, v173
	v_cvt_pk_bf16_f32 v181, v174, v175
	v_cvt_pk_bf16_f32 v182, v176, v177
	v_cvt_pk_bf16_f32 v183, v178, v179
	global_store_dwordx4 v[142:143], v[180:183], off
	v_lshl_add_u64 v[140:141], v[140:141], 0, s[6:7]
	v_lshl_add_u64 v[142:143], v[142:143], 0, s[6:7]
	v_pk_mul_f32 v[144:145], v[46:47], v[246:247] op_sel_hi:[1,0]
	v_pk_mul_f32 v[146:147], v[48:49], v[246:247] op_sel_hi:[1,0]
	v_pk_mul_f32 v[148:149], v[42:43], v[246:247] op_sel_hi:[1,0]
	v_pk_mul_f32 v[150:151], v[44:45], v[246:247] op_sel_hi:[1,0]
	v_cvt_pk_bf16_f32 v152, v144, v145
	v_cvt_pk_bf16_f32 v153, v146, v147
	v_cvt_pk_bf16_f32 v154, v148, v149
	v_cvt_pk_bf16_f32 v155, v150, v151
	global_store_dwordx4 v[140:141], v[152:155], off
	v_pk_mul_f32 v[172:173], v[38:39], v[246:247] op_sel_hi:[1,0]
	v_pk_mul_f32 v[174:175], v[40:41], v[246:247] op_sel_hi:[1,0]
	v_pk_mul_f32 v[176:177], v[34:35], v[246:247] op_sel_hi:[1,0]
	v_pk_mul_f32 v[178:179], v[36:37], v[246:247] op_sel_hi:[1,0]
	v_cvt_pk_bf16_f32 v180, v172, v173
	v_cvt_pk_bf16_f32 v181, v174, v175
	v_cvt_pk_bf16_f32 v182, v176, v177
	v_cvt_pk_bf16_f32 v183, v178, v179
	global_store_dwordx4 v[142:143], v[180:183], off
	v_lshl_add_u64 v[140:141], v[140:141], 0, s[6:7]
	v_lshl_add_u64 v[142:143], v[142:143], 0, s[6:7]
	v_pk_mul_f32 v[144:145], v[30:31], v[248:249] op_sel_hi:[1,0]
	v_pk_mul_f32 v[146:147], v[32:33], v[248:249] op_sel_hi:[1,0]
	v_pk_mul_f32 v[148:149], v[26:27], v[248:249] op_sel_hi:[1,0]
	v_pk_mul_f32 v[150:151], v[28:29], v[248:249] op_sel_hi:[1,0]
	v_cvt_pk_bf16_f32 v152, v144, v145
	v_cvt_pk_bf16_f32 v153, v146, v147
	v_cvt_pk_bf16_f32 v154, v148, v149
	v_cvt_pk_bf16_f32 v155, v150, v151
	global_store_dwordx4 v[140:141], v[152:155], off
	v_pk_mul_f32 v[172:173], v[22:23], v[248:249] op_sel_hi:[1,0]
	v_pk_mul_f32 v[174:175], v[24:25], v[248:249] op_sel_hi:[1,0]
	v_pk_mul_f32 v[176:177], v[18:19], v[248:249] op_sel_hi:[1,0]
	v_pk_mul_f32 v[178:179], v[20:21], v[248:249] op_sel_hi:[1,0]
	v_cvt_pk_bf16_f32 v180, v172, v173
	v_cvt_pk_bf16_f32 v181, v174, v175
	v_cvt_pk_bf16_f32 v182, v176, v177
	v_cvt_pk_bf16_f32 v183, v178, v179
	global_store_dwordx4 v[142:143], v[180:183], off
	v_lshl_add_u64 v[140:141], v[140:141], 0, s[6:7]
	v_lshl_add_u64 v[142:143], v[142:143], 0, s[6:7]
	v_pk_mul_f32 v[144:145], v[14:15], v[252:253] op_sel_hi:[1,0]
	v_pk_mul_f32 v[146:147], v[16:17], v[252:253] op_sel_hi:[1,0]
	v_pk_mul_f32 v[148:149], v[10:11], v[252:253] op_sel_hi:[1,0]
	v_pk_mul_f32 v[150:151], v[12:13], v[252:253] op_sel_hi:[1,0]
	v_cvt_pk_bf16_f32 v152, v144, v145
	v_cvt_pk_bf16_f32 v153, v146, v147
	v_cvt_pk_bf16_f32 v154, v148, v149
	v_cvt_pk_bf16_f32 v155, v150, v151
	global_store_dwordx4 v[140:141], v[152:155], off
	v_pk_mul_f32 v[172:173], v[6:7], v[252:253] op_sel_hi:[1,0]
	v_pk_mul_f32 v[174:175], v[8:9], v[252:253] op_sel_hi:[1,0]
	v_pk_mul_f32 v[176:177], v[2:3], v[252:253] op_sel_hi:[1,0]
	v_pk_mul_f32 v[178:179], v[4:5], v[252:253] op_sel_hi:[1,0]
	v_cvt_pk_bf16_f32 v180, v172, v173
	v_cvt_pk_bf16_f32 v181, v174, v175
	v_cvt_pk_bf16_f32 v182, v176, v177
	v_cvt_pk_bf16_f32 v183, v178, v179
	global_store_dwordx4 v[142:143], v[180:183], off
	s_branch .Lmy_epi_done
.Lmy_epi_relu2:
	v_pk_mul_f32 v[144:145], v[126:127], v[236:237] op_sel_hi:[1,0]
	v_pk_mul_f32 v[146:147], v[128:129], v[236:237] op_sel_hi:[1,0]
	v_pk_mul_f32 v[148:149], v[122:123], v[236:237] op_sel_hi:[1,0]
	v_pk_mul_f32 v[150:151], v[124:125], v[236:237] op_sel_hi:[1,0]
	v_max_f32_e32 v144, 0, v144
	v_max_f32_e32 v145, 0, v145
	v_max_f32_e32 v146, 0, v146
	v_max_f32_e32 v147, 0, v147
	v_max_f32_e32 v148, 0, v148
	v_max_f32_e32 v149, 0, v149
	v_max_f32_e32 v150, 0, v150
	v_max_f32_e32 v151, 0, v151
	v_pk_mul_f32 v[144:145], v[144:145], v[144:145]
	v_pk_mul_f32 v[146:147], v[146:147], v[146:147]
	v_pk_mul_f32 v[148:149], v[148:149], v[148:149]
	v_pk_mul_f32 v[150:151], v[150:151], v[150:151]
	v_cvt_pk_bf16_f32 v152, v144, v145
	v_cvt_pk_bf16_f32 v153, v146, v147
	v_cvt_pk_bf16_f32 v154, v148, v149
	v_cvt_pk_bf16_f32 v155, v150, v151
	global_store_dwordx4 v[140:141], v[152:155], off
	v_pk_mul_f32 v[172:173], v[118:119], v[236:237] op_sel_hi:[1,0]
	v_pk_mul_f32 v[174:175], v[120:121], v[236:237] op_sel_hi:[1,0]
	v_pk_mul_f32 v[176:177], v[114:115], v[236:237] op_sel_hi:[1,0]
	v_pk_mul_f32 v[178:179], v[116:117], v[236:237] op_sel_hi:[1,0]
	v_max_f32_e32 v172, 0, v172
	v_max_f32_e32 v173, 0, v173
	v_max_f32_e32 v174, 0, v174
	v_max_f32_e32 v175, 0, v175
	v_max_f32_e32 v176, 0, v176
	v_max_f32_e32 v177, 0, v177
	v_max_f32_e32 v178, 0, v178
	v_max_f32_e32 v179, 0, v179
	v_pk_mul_f32 v[172:173], v[172:173], v[172:173]
	v_pk_mul_f32 v[174:175], v[174:175], v[174:175]
; #define PG8_GAS __attribute__((address_space(1)))
; __device__ __forceinline__ unsigned cvt_pk_bf16(float lo, float hi) { unsigned r; asm volatile("v_cvt_pk_bf16_f32 %0, %1, %2" : "=v"(r) : "v"(lo), "v"(hi)); return r; }
;     __device__ __forceinline__ void operator()(const f32x4 (&acc)[2][2][4][2], const Unit& u, int wr, int wc, int fr, int fq) const {
;     ...
;                 for (int bj = 0; bj < 2; ++bj) { f32x4 v0 = acc[ai][bj][m][0] * rs, v1 = acc[ai][bj][m][1] * rs;
;                     if (ACT == 1) {
; #pragma unroll
;                         for (int e = 0; e < 4; ++e) { const float a = fmaxf(v0[e], 0.f), b = fmaxf(v1[e], 0.f); v0[e] = a * a; v1[e] = b * b; } }
;                     u32x4 w; w.x = cvt_pk_bf16(v0[0], v0[1]); w.y = cvt_pk_bf16(v0[2], v0[3]); w.z = cvt_pk_bf16(v1[0], v1[1]); w.w = cvt_pk_bf16(v1[2], v1[3]);
;                     *(PG8_GAS u32x4*)(rowp + bj * HALF) = w; } }
	v_pk_mul_f32 v[176:177], v[176:177], v[176:177]
	v_pk_mul_f32 v[178:179], v[178:179], v[178:179]
	v_cvt_pk_bf16_f32 v180, v172, v173
	v_cvt_pk_bf16_f32 v181, v174, v175
	v_cvt_pk_bf16_f32 v182, v176, v177
	v_cvt_pk_bf16_f32 v183, v178, v179
	global_store_dwordx4 v[142:143], v[180:183], off
	v_lshl_add_u64 v[140:141], v[140:141], 0, s[6:7]
	v_lshl_add_u64 v[142:143], v[142:143], 0, s[6:7]
	v_pk_mul_f32 v[144:145], v[110:111], v[238:239] op_sel_hi:[1,0]
	v_pk_mul_f32 v[146:147], v[112:113], v[238:239] op_sel_hi:[1,0]
	v_pk_mul_f32 v[148:149], v[106:107], v[238:239] op_sel_hi:[1,0]
	v_pk_mul_f32 v[150:151], v[108:109], v[238:239] op_sel_hi:[1,0]
	v_max_f32_e32 v144, 0, v144
	v_max_f32_e32 v145, 0, v145
	v_max_f32_e32 v146, 0, v146
	v_max_f32_e32 v147, 0, v147
	v_max_f32_e32 v148, 0, v148
	v_max_f32_e32 v149, 0, v149
	v_max_f32_e32 v150, 0, v150
	v_max_f32_e32 v151, 0, v151
	v_pk_mul_f32 v[144:145], v[144:145], v[144:145]
	v_pk_mul_f32 v[146:147], v[146:147], v[146:147]
	v_pk_mul_f32 v[148:149], v[148:149], v[148:149]
	v_pk_mul_f32 v[150:151], v[150:151], v[150:151]
	v_cvt_pk_bf16_f32 v152, v144, v145
	v_cvt_pk_bf16_f32 v153, v146, v147
	v_cvt_pk_bf16_f32 v154, v148, v149
	v_cvt_pk_bf16_f32 v155, v150, v151
	global_store_dwordx4 v[140:141], v[152:155], off
	v_pk_mul_f32 v[172:173], v[102:103], v[238:239] op_sel_hi:[1,0]
	v_pk_mul_f32 v[174:175], v[104:105], v[238:239] op_sel_hi:[1,0]
	v_pk_mul_f32 v[176:177], v[98:99], v[238:239] op_sel_hi:[1,0]
	v_pk_mul_f32 v[178:179], v[100:101], v[238:239] op_sel_hi:[1,0]
	v_max_f32_e32 v172, 0, v172
	v_max_f32_e32 v173, 0, v173
	v_max_f32_e32 v174, 0, v174
	v_max_f32_e32 v175, 0, v175
	v_max_f32_e32 v176, 0, v176
	v_max_f32_e32 v177, 0, v177
	v_max_f32_e32 v178, 0, v178
	v_max_f32_e32 v179, 0, v179
	v_pk_mul_f32 v[172:173], v[172:173], v[172:173]
	v_pk_mul_f32 v[174:175], v[174:175], v[174:175]
	v_pk_mul_f32 v[176:177], v[176:177], v[176:177]
	v_pk_mul_f32 v[178:179], v[178:179], v[178:179]
	v_cvt_pk_bf16_f32 v180, v172, v173
	v_cvt_pk_bf16_f32 v181, v174, v175
	v_cvt_pk_bf16_f32 v182, v176, v177
	v_cvt_pk_bf16_f32 v183, v178, v179
	global_store_dwordx4 v[142:143], v[180:183], off
	v_lshl_add_u64 v[140:141], v[140:141], 0, s[6:7]
	v_lshl_add_u64 v[142:143], v[142:143], 0, s[6:7]
	v_pk_mul_f32 v[144:145], v[94:95], v[240:241] op_sel_hi:[1,0]
	v_pk_mul_f32 v[146:147], v[96:97], v[240:241] op_sel_hi:[1,0]
	v_pk_mul_f32 v[148:149], v[90:91], v[240:241] op_sel_hi:[1,0]
	v_pk_mul_f32 v[150:151], v[92:93], v[240:241] op_sel_hi:[1,0]
	v_max_f32_e32 v144, 0, v144
	v_max_f32_e32 v145, 0, v145
	v_max_f32_e32 v146, 0, v146
	v_max_f32_e32 v147, 0, v147
	v_max_f32_e32 v148, 0, v148
	v_max_f32_e32 v149, 0, v149
	v_max_f32_e32 v150, 0, v150
	v_max_f32_e32 v151, 0, v151
	v_pk_mul_f32 v[144:145], v[144:145], v[144:145]
	v_pk_mul_f32 v[146:147], v[146:147], v[146:147]
	v_pk_mul_f32 v[148:149], v[148:149], v[148:149]
	v_pk_mul_f32 v[150:151], v[150:151], v[150:151]
	v_cvt_pk_bf16_f32 v152, v144, v145
	v_cvt_pk_bf16_f32 v153, v146, v147
	v_cvt_pk_bf16_f32 v154, v148, v149
	v_cvt_pk_bf16_f32 v155, v150, v151
	global_store_dwordx4 v[140:141], v[152:155], off
	v_pk_mul_f32 v[172:173], v[86:87], v[240:241] op_sel_hi:[1,0]
	v_pk_mul_f32 v[174:175], v[88:89], v[240:241] op_sel_hi:[1,0]
	v_pk_mul_f32 v[176:177], v[82:83], v[240:241] op_sel_hi:[1,0]
	v_pk_mul_f32 v[178:179], v[84:85], v[240:241] op_sel_hi:[1,0]
	v_max_f32_e32 v172, 0, v172
	v_max_f32_e32 v173, 0, v173
	v_max_f32_e32 v174, 0, v174
	v_max_f32_e32 v175, 0, v175
	v_max_f32_e32 v176, 0, v176
	v_max_f32_e32 v177, 0, v177
	v_max_f32_e32 v178, 0, v178
	v_max_f32_e32 v179, 0, v179
	v_pk_mul_f32 v[172:173], v[172:173], v[172:173]
	v_pk_mul_f32 v[174:175], v[174:175], v[174:175]
	v_pk_mul_f32 v[176:177], v[176:177], v[176:177]
	v_pk_mul_f32 v[178:179], v[178:179], v[178:179]
	v_cvt_pk_bf16_f32 v180, v172, v173
	v_cvt_pk_bf16_f32 v181, v174, v175
	v_cvt_pk_bf16_f32 v182, v176, v177
	v_cvt_pk_bf16_f32 v183, v178, v179
	global_store_dwordx4 v[142:143], v[180:183], off
	v_lshl_add_u64 v[140:141], v[140:141], 0, s[6:7]
	v_lshl_add_u64 v[142:143], v[142:143], 0, s[6:7]
	v_pk_mul_f32 v[144:145], v[78:79], v[242:243] op_sel_hi:[1,0]
	v_pk_mul_f32 v[146:147], v[80:81], v[242:243] op_sel_hi:[1,0]
	v_pk_mul_f32 v[148:149], v[74:75], v[242:243] op_sel_hi:[1,0]
	v_pk_mul_f32 v[150:151], v[76:77], v[242:243] op_sel_hi:[1,0]
	v_max_f32_e32 v144, 0, v144
	v_max_f32_e32 v145, 0, v145
	v_max_f32_e32 v146, 0, v146
	v_max_f32_e32 v147, 0, v147
	v_max_f32_e32 v148, 0, v148
	v_max_f32_e32 v149, 0, v149
	v_max_f32_e32 v150, 0, v150
	v_max_f32_e32 v151, 0, v151
	v_pk_mul_f32 v[144:145], v[144:145], v[144:145]
	v_pk_mul_f32 v[146:147], v[146:147], v[146:147]
	v_pk_mul_f32 v[148:149], v[148:149], v[148:149]
	v_pk_mul_f32 v[150:151], v[150:151], v[150:151]
	v_cvt_pk_bf16_f32 v152, v144, v145
	v_cvt_pk_bf16_f32 v153, v146, v147
	v_cvt_pk_bf16_f32 v154, v148, v149
	v_cvt_pk_bf16_f32 v155, v150, v151
	global_store_dwordx4 v[140:141], v[152:155], off
	v_pk_mul_f32 v[172:173], v[70:71], v[242:243] op_sel_hi:[1,0]
	v_pk_mul_f32 v[174:175], v[72:73], v[242:243] op_sel_hi:[1,0]
	v_pk_mul_f32 v[176:177], v[66:67], v[242:243] op_sel_hi:[1,0]
	v_pk_mul_f32 v[178:179], v[68:69], v[242:243] op_sel_hi:[1,0]
	v_max_f32_e32 v172, 0, v172
	v_max_f32_e32 v173, 0, v173
	v_max_f32_e32 v174, 0, v174
	v_max_f32_e32 v175, 0, v175
	v_max_f32_e32 v176, 0, v176
	v_max_f32_e32 v177, 0, v177
	v_max_f32_e32 v178, 0, v178
	v_max_f32_e32 v179, 0, v179
	v_pk_mul_f32 v[172:173], v[172:173], v[172:173]
	v_pk_mul_f32 v[174:175], v[174:175], v[174:175]
	v_pk_mul_f32 v[176:177], v[176:177], v[176:177]
	v_pk_mul_f32 v[178:179], v[178:179], v[178:179]
; #define PG8_GAS __attribute__((address_space(1)))
; __device__ __forceinline__ unsigned cvt_pk_bf16(float lo, float hi) { unsigned r; asm volatile("v_cvt_pk_bf16_f32 %0, %1, %2" : "=v"(r) : "v"(lo), "v"(hi)); return r; }
;     __device__ __forceinline__ void operator()(const f32x4 (&acc)[2][2][4][2], const Unit& u, int wr, int wc, int fr, int fq) const {
;     ...
;                 for (int bj = 0; bj < 2; ++bj) { f32x4 v0 = acc[ai][bj][m][0] * rs, v1 = acc[ai][bj][m][1] * rs;
;                     if (ACT == 1) {
; #pragma unroll
;                         for (int e = 0; e < 4; ++e) { const float a = fmaxf(v0[e], 0.f), b = fmaxf(v1[e], 0.f); v0[e] = a * a; v1[e] = b * b; } }
;                     u32x4 w; w.x = cvt_pk_bf16(v0[0], v0[1]); w.y = cvt_pk_bf16(v0[2], v0[3]); w.z = cvt_pk_bf16(v1[0], v1[1]); w.w = cvt_pk_bf16(v1[2], v1[3]);
;                     *(PG8_GAS u32x4*)(rowp + bj * HALF) = w; } }
	v_cvt_pk_bf16_f32 v180, v172, v173
	v_cvt_pk_bf16_f32 v181, v174, v175
	v_cvt_pk_bf16_f32 v182, v176, v177
	v_cvt_pk_bf16_f32 v183, v178, v179
	global_store_dwordx4 v[142:143], v[180:183], off
	v_lshl_add_u64 v[140:141], v[140:141], 0, s[4:5]
	v_lshl_add_u64 v[142:143], v[142:143], 0, s[4:5]
	v_pk_mul_f32 v[144:145], v[62:63], v[244:245] op_sel_hi:[1,0]
	v_pk_mul_f32 v[146:147], v[64:65], v[244:245] op_sel_hi:[1,0]
	v_pk_mul_f32 v[148:149], v[58:59], v[244:245] op_sel_hi:[1,0]
	v_pk_mul_f32 v[150:151], v[60:61], v[244:245] op_sel_hi:[1,0]
	v_max_f32_e32 v144, 0, v144
	v_max_f32_e32 v145, 0, v145
	v_max_f32_e32 v146, 0, v146
	v_max_f32_e32 v147, 0, v147
	v_max_f32_e32 v148, 0, v148
	v_max_f32_e32 v149, 0, v149
	v_max_f32_e32 v150, 0, v150
	v_max_f32_e32 v151, 0, v151
	v_pk_mul_f32 v[144:145], v[144:145], v[144:145]
	v_pk_mul_f32 v[146:147], v[146:147], v[146:147]
	v_pk_mul_f32 v[148:149], v[148:149], v[148:149]
	v_pk_mul_f32 v[150:151], v[150:151], v[150:151]
	v_cvt_pk_bf16_f32 v152, v144, v145
	v_cvt_pk_bf16_f32 v153, v146, v147
	v_cvt_pk_bf16_f32 v154, v148, v149
	v_cvt_pk_bf16_f32 v155, v150, v151
	global_store_dwordx4 v[140:141], v[152:155], off
	v_pk_mul_f32 v[172:173], v[54:55], v[244:245] op_sel_hi:[1,0]
	v_pk_mul_f32 v[174:175], v[56:57], v[244:245] op_sel_hi:[1,0]
	v_pk_mul_f32 v[176:177], v[50:51], v[244:245] op_sel_hi:[1,0]
	v_pk_mul_f32 v[178:179], v[52:53], v[244:245] op_sel_hi:[1,0]
	v_max_f32_e32 v172, 0, v172
	v_max_f32_e32 v173, 0, v173
	v_max_f32_e32 v174, 0, v174
	v_max_f32_e32 v175, 0, v175
	v_max_f32_e32 v176, 0, v176
	v_max_f32_e32 v177, 0, v177
	v_max_f32_e32 v178, 0, v178
	v_max_f32_e32 v179, 0, v179
	v_pk_mul_f32 v[172:173], v[172:173], v[172:173]
	v_pk_mul_f32 v[174:175], v[174:175], v[174:175]
	v_pk_mul_f32 v[176:177], v[176:177], v[176:177]
	v_pk_mul_f32 v[178:179], v[178:179], v[178:179]
	v_cvt_pk_bf16_f32 v180, v172, v173
	v_cvt_pk_bf16_f32 v181, v174, v175
	v_cvt_pk_bf16_f32 v182, v176, v177
	v_cvt_pk_bf16_f32 v183, v178, v179
	global_store_dwordx4 v[142:143], v[180:183], off
	v_lshl_add_u64 v[140:141], v[140:141], 0, s[6:7]
	v_lshl_add_u64 v[142:143], v[142:143], 0, s[6:7]
	v_pk_mul_f32 v[144:145], v[46:47], v[246:247] op_sel_hi:[1,0]
	v_pk_mul_f32 v[146:147], v[48:49], v[246:247] op_sel_hi:[1,0]
	v_pk_mul_f32 v[148:149], v[42:43], v[246:247] op_sel_hi:[1,0]
	v_pk_mul_f32 v[150:151], v[44:45], v[246:247] op_sel_hi:[1,0]
	v_max_f32_e32 v144, 0, v144
	v_max_f32_e32 v145, 0, v145
	v_max_f32_e32 v146, 0, v146
	v_max_f32_e32 v147, 0, v147
	v_max_f32_e32 v148, 0, v148
	v_max_f32_e32 v149, 0, v149
	v_max_f32_e32 v150, 0, v150
	v_max_f32_e32 v151, 0, v151
	v_pk_mul_f32 v[144:145], v[144:145], v[144:145]
	v_pk_mul_f32 v[146:147], v[146:147], v[146:147]
	v_pk_mul_f32 v[148:149], v[148:149], v[148:149]
	v_pk_mul_f32 v[150:151], v[150:151], v[150:151]
	v_cvt_pk_bf16_f32 v152, v144, v145
	v_cvt_pk_bf16_f32 v153, v146, v147
	v_cvt_pk_bf16_f32 v154, v148, v149
	v_cvt_pk_bf16_f32 v155, v150, v151
	global_store_dwordx4 v[140:141], v[152:155], off
	v_pk_mul_f32 v[172:173], v[38:39], v[246:247] op_sel_hi:[1,0]
	v_pk_mul_f32 v[174:175], v[40:41], v[246:247] op_sel_hi:[1,0]
	v_pk_mul_f32 v[176:177], v[34:35], v[246:247] op_sel_hi:[1,0]
	v_pk_mul_f32 v[178:179], v[36:37], v[246:247] op_sel_hi:[1,0]
	v_max_f32_e32 v172, 0, v172
	v_max_f32_e32 v173, 0, v173
	v_max_f32_e32 v174, 0, v174
	v_max_f32_e32 v175, 0, v175
	v_max_f32_e32 v176, 0, v176
	v_max_f32_e32 v177, 0, v177
	v_max_f32_e32 v178, 0, v178
	v_max_f32_e32 v179, 0, v179
	v_pk_mul_f32 v[172:173], v[172:173], v[172:173]
	v_pk_mul_f32 v[174:175], v[174:175], v[174:175]
	v_pk_mul_f32 v[176:177], v[176:177], v[176:177]
	v_pk_mul_f32 v[178:179], v[178:179], v[178:179]
	v_cvt_pk_bf16_f32 v180, v172, v173
	v_cvt_pk_bf16_f32 v181, v174, v175
	v_cvt_pk_bf16_f32 v182, v176, v177
; #define PG8_GAS __attribute__((address_space(1)))
; __device__ __forceinline__ unsigned cvt_pk_bf16(float lo, float hi) { unsigned r; asm volatile("v_cvt_pk_bf16_f32 %0, %1, %2" : "=v"(r) : "v"(lo), "v"(hi)); return r; }
;     __device__ __forceinline__ void operator()(const f32x4 (&acc)[2][2][4][2], const Unit& u, int wr, int wc, int fr, int fq) const {
;     ...
;                 for (int bj = 0; bj < 2; ++bj) { f32x4 v0 = acc[ai][bj][m][0] * rs, v1 = acc[ai][bj][m][1] * rs;
;                     if (ACT == 1) {
; #pragma unroll
;                         for (int e = 0; e < 4; ++e) { const float a = fmaxf(v0[e], 0.f), b = fmaxf(v1[e], 0.f); v0[e] = a * a; v1[e] = b * b; } }
;                     u32x4 w; w.x = cvt_pk_bf16(v0[0], v0[1]); w.y = cvt_pk_bf16(v0[2], v0[3]); w.z = cvt_pk_bf16(v1[0], v1[1]); w.w = cvt_pk_bf16(v1[2], v1[3]);
;                     *(PG8_GAS u32x4*)(rowp + bj * HALF) = w; } }
	v_cvt_pk_bf16_f32 v183, v178, v179
	global_store_dwordx4 v[142:143], v[180:183], off
	v_lshl_add_u64 v[140:141], v[140:141], 0, s[6:7]
	v_lshl_add_u64 v[142:143], v[142:143], 0, s[6:7]
	v_pk_mul_f32 v[144:145], v[30:31], v[248:249] op_sel_hi:[1,0]
	v_pk_mul_f32 v[146:147], v[32:33], v[248:249] op_sel_hi:[1,0]
	v_pk_mul_f32 v[148:149], v[26:27], v[248:249] op_sel_hi:[1,0]
	v_pk_mul_f32 v[150:151], v[28:29], v[248:249] op_sel_hi:[1,0]
	v_max_f32_e32 v144, 0, v144
	v_max_f32_e32 v145, 0, v145
	v_max_f32_e32 v146, 0, v146
	v_max_f32_e32 v147, 0, v147
	v_max_f32_e32 v148, 0, v148
	v_max_f32_e32 v149, 0, v149
	v_max_f32_e32 v150, 0, v150
	v_max_f32_e32 v151, 0, v151
	v_pk_mul_f32 v[144:145], v[144:145], v[144:145]
	v_pk_mul_f32 v[146:147], v[146:147], v[146:147]
	v_pk_mul_f32 v[148:149], v[148:149], v[148:149]
	v_pk_mul_f32 v[150:151], v[150:151], v[150:151]
	v_cvt_pk_bf16_f32 v152, v144, v145
	v_cvt_pk_bf16_f32 v153, v146, v147
	v_cvt_pk_bf16_f32 v154, v148, v149
	v_cvt_pk_bf16_f32 v155, v150, v151
	global_store_dwordx4 v[140:141], v[152:155], off
	v_pk_mul_f32 v[172:173], v[22:23], v[248:249] op_sel_hi:[1,0]
	v_pk_mul_f32 v[174:175], v[24:25], v[248:249] op_sel_hi:[1,0]
	v_pk_mul_f32 v[176:177], v[18:19], v[248:249] op_sel_hi:[1,0]
	v_pk_mul_f32 v[178:179], v[20:21], v[248:249] op_sel_hi:[1,0]
	v_max_f32_e32 v172, 0, v172
	v_max_f32_e32 v173, 0, v173
	v_max_f32_e32 v174, 0, v174
	v_max_f32_e32 v175, 0, v175
	v_max_f32_e32 v176, 0, v176
	v_max_f32_e32 v177, 0, v177
	v_max_f32_e32 v178, 0, v178
	v_max_f32_e32 v179, 0, v179
	v_pk_mul_f32 v[172:173], v[172:173], v[172:173]
	v_pk_mul_f32 v[174:175], v[174:175], v[174:175]
	v_pk_mul_f32 v[176:177], v[176:177], v[176:177]
	v_pk_mul_f32 v[178:179], v[178:179], v[178:179]
	v_cvt_pk_bf16_f32 v180, v172, v173
	v_cvt_pk_bf16_f32 v181, v174, v175
	v_cvt_pk_bf16_f32 v182, v176, v177
	v_cvt_pk_bf16_f32 v183, v178, v179
	global_store_dwordx4 v[142:143], v[180:183], off
	v_lshl_add_u64 v[140:141], v[140:141], 0, s[6:7]
	v_lshl_add_u64 v[142:143], v[142:143], 0, s[6:7]
	v_pk_mul_f32 v[144:145], v[14:15], v[252:253] op_sel_hi:[1,0]
	v_pk_mul_f32 v[146:147], v[16:17], v[252:253] op_sel_hi:[1,0]
	v_pk_mul_f32 v[148:149], v[10:11], v[252:253] op_sel_hi:[1,0]
	v_pk_mul_f32 v[150:151], v[12:13], v[252:253] op_sel_hi:[1,0]
	v_max_f32_e32 v144, 0, v144
	v_max_f32_e32 v145, 0, v145
	v_max_f32_e32 v146, 0, v146
	v_max_f32_e32 v147, 0, v147
	v_max_f32_e32 v148, 0, v148
	v_max_f32_e32 v149, 0, v149
	v_max_f32_e32 v150, 0, v150
	v_max_f32_e32 v151, 0, v151
	v_pk_mul_f32 v[144:145], v[144:145], v[144:145]
	v_pk_mul_f32 v[146:147], v[146:147], v[146:147]
	v_pk_mul_f32 v[148:149], v[148:149], v[148:149]
	v_pk_mul_f32 v[150:151], v[150:151], v[150:151]
	v_cvt_pk_bf16_f32 v152, v144, v145
	v_cvt_pk_bf16_f32 v153, v146, v147
	v_cvt_pk_bf16_f32 v154, v148, v149
	v_cvt_pk_bf16_f32 v155, v150, v151
	global_store_dwordx4 v[140:141], v[152:155], off
	v_pk_mul_f32 v[172:173], v[6:7], v[252:253] op_sel_hi:[1,0]
	v_pk_mul_f32 v[174:175], v[8:9], v[252:253] op_sel_hi:[1,0]
	v_pk_mul_f32 v[176:177], v[2:3], v[252:253] op_sel_hi:[1,0]
	v_pk_mul_f32 v[178:179], v[4:5], v[252:253] op_sel_hi:[1,0]
	v_max_f32_e32 v172, 0, v172
	v_max_f32_e32 v173, 0, v173
	v_max_f32_e32 v174, 0, v174
	v_max_f32_e32 v175, 0, v175
	v_max_f32_e32 v176, 0, v176
	v_max_f32_e32 v177, 0, v177
	v_max_f32_e32 v178, 0, v178
	v_max_f32_e32 v179, 0, v179
	v_pk_mul_f32 v[172:173], v[172:173], v[172:173]
	v_pk_mul_f32 v[174:175], v[174:175], v[174:175]
	v_pk_mul_f32 v[176:177], v[176:177], v[176:177]
	v_pk_mul_f32 v[178:179], v[178:179], v[178:179]
	v_cvt_pk_bf16_f32 v180, v172, v173
	v_cvt_pk_bf16_f32 v181, v174, v175
	v_cvt_pk_bf16_f32 v182, v176, v177
	v_cvt_pk_bf16_f32 v183, v178, v179
	global_store_dwordx4 v[142:143], v[180:183], off
